# norm1/norm2: pipelined rows, lane-pair merge to 16-B write-through (sc1) H stores
# speedup vs baseline: 1.0547x; 1.0013x over previous
.LBB0_172:
	s_or_b64 exec, exec, s[0:1]
	s_add_i32 s0, 0, 0x23f00
	v_mov_b32_e32 v0, s0
	s_add_i32 s0, 0, 0x23f28
	v_mov_b32_e32 v2, s0
	s_add_i32 s0, 0, 0x23fa8
	s_mov_b32 s2, -1
	v_mov_b32_e32 v4, s0
	s_waitcnt lgkmcnt(0)
	s_barrier
	ds_read_b64 v[0:1], v0
	ds_read_b64 v[2:3], v2
	ds_read_b64 v[4:5], v4
	s_cmpk_lt_i32 s84, 0x4000
	s_cselect_b64 s[0:1], -1, 0
	s_waitcnt lgkmcnt(0)
	v_readfirstlane_b32 s24, v0
	v_readfirstlane_b32 s25, v1
	v_readfirstlane_b32 s4, v2
	v_readfirstlane_b32 s5, v3
	v_readfirstlane_b32 s3, v4
	s_cmpk_gt_i32 s84, 0x3fff
	v_readfirstlane_b32 s6, v5
	s_cbranch_scc1 .LBB0_177
	s_cmpk_lg_i32 s76, 0x100
	s_cbranch_scc1 .Lnorm1_generic
	s_ashr_i32 s85, s84, 31
	s_lshl_b64 s[10:11], s[84:85], 12
	s_add_u32 s10, s24, s10
	s_addc_u32 s11, s25, s11
	s_lshl_b64 s[12:13], s[84:85], 11
	s_add_u32 s12, s3, s12
	s_addc_u32 s13, s6, s13
	s_add_u32 s12, s12, 0x2800000
	s_addc_u32 s13, s13, 0
	s_add_u32 s14, s3, 0x1c00000
	s_addc_u32 s15, s6, 0
	s_add_u32 s16, s14, 0x1000
	s_addc_u32 s17, s15, 0
	v_mbcnt_lo_u32_b32 v176, -1, 0
	v_mbcnt_hi_u32_b32 v176, -1, v176
	v_lshlrev_b32_e32 v172, 4, v176
	v_lshlrev_b32_e32 v173, 3, v176
	v_xor_b32_e32 v174, 16, v176
	v_xor_b32_e32 v175, 32, v176
	v_lshlrev_b32_e32 v174, 2, v174
	v_lshlrev_b32_e32 v175, 2, v175
	v_and_b32_e32 v177, 1, v176
	v_cmp_eq_u32_e32 vcc, 1, v177
	v_mul_u32_u24_e32 v177, 0x1f8, v177
	v_add_u32_e32 v177, v177, v173
	global_load_dwordx4 v[0:3], v172, s[10:11]
	global_load_dwordx4 v[4:7], v172, s[10:11] offset:1024
	global_load_dwordx4 v[8:11], v172, s[10:11] offset:2048
	global_load_dwordx4 v[12:15], v172, s[10:11] offset:3072
	s_add_u32 s10, s10, 0x800000
	s_addc_u32 s11, s11, 0
	global_load_dwordx4 v[16:19], v172, s[10:11]
	global_load_dwordx4 v[20:23], v172, s[10:11] offset:1024
	global_load_dwordx4 v[24:27], v172, s[10:11] offset:2048
	global_load_dwordx4 v[28:31], v172, s[10:11] offset:3072
	s_add_u32 s10, s10, 0x800000
	s_addc_u32 s11, s11, 0
	global_load_dwordx4 v[64:67], v172, s[4:5]
	global_load_dwordx4 v[68:71], v172, s[4:5] offset:1024
	global_load_dwordx4 v[72:75], v172, s[4:5] offset:2048
	global_load_dwordx4 v[76:79], v172, s[4:5] offset:3072
	global_load_dwordx4 v[80:83], v172, s[16:17]
	global_load_dwordx4 v[84:87], v172, s[16:17] offset:1024
	global_load_dwordx4 v[88:91], v172, s[16:17] offset:2048
	global_load_dwordx4 v[92:95], v172, s[16:17] offset:3072
	global_load_dwordx4 v[112:115], v172, s[14:15]
	global_load_dwordx4 v[116:119], v172, s[14:15] offset:1024
	global_load_dwordx4 v[120:123], v172, s[14:15] offset:2048
	global_load_dwordx4 v[124:127], v172, s[14:15] offset:3072
	s_add_u32 s16, s16, 0x6000
	s_addc_u32 s17, s17, 0
	s_add_u32 s14, s14, 0x6000
	s_addc_u32 s15, s15, 0
	global_load_dwordx4 v[32:35], v172, s[10:11]
	global_load_dwordx4 v[36:39], v172, s[10:11] offset:1024
	global_load_dwordx4 v[40:43], v172, s[10:11] offset:2048
	global_load_dwordx4 v[44:47], v172, s[10:11] offset:3072
	s_add_u32 s10, s10, 0x800000
	s_addc_u32 s11, s11, 0
	global_load_dwordx4 v[48:51], v172, s[10:11]
	global_load_dwordx4 v[52:55], v172, s[10:11] offset:1024
	global_load_dwordx4 v[56:59], v172, s[10:11] offset:2048
	global_load_dwordx4 v[60:63], v172, s[10:11] offset:3072
	s_add_u32 s10, s10, 0x800000
	s_addc_u32 s11, s11, 0
	s_waitcnt vmcnt(24)
	v_mul_f32_e32 v156, v0, v0
	v_mul_f32_e32 v157, v4, v4
	v_mul_f32_e32 v158, v8, v8
	v_mul_f32_e32 v159, v12, v12
	v_fmac_f32_e32 v156, v1, v1
	v_fmac_f32_e32 v157, v5, v5
	v_fmac_f32_e32 v158, v9, v9
	v_fmac_f32_e32 v159, v13, v13
	v_fmac_f32_e32 v156, v2, v2
	v_fmac_f32_e32 v157, v6, v6
	v_fmac_f32_e32 v158, v10, v10
	v_fmac_f32_e32 v159, v14, v14
	v_fmac_f32_e32 v156, v3, v3
	v_fmac_f32_e32 v157, v7, v7
	v_fmac_f32_e32 v158, v11, v11
	v_fmac_f32_e32 v159, v15, v15
	v_add_f32_e32 v156, v156, v157
	v_add_f32_e32 v158, v158, v159
	v_add_f32_e32 v144, v156, v158
	global_load_dwordx4 v[96:99], v172, s[16:17]
	global_load_dwordx4 v[100:103], v172, s[16:17] offset:1024
	global_load_dwordx4 v[104:107], v172, s[16:17] offset:2048
	global_load_dwordx4 v[108:111], v172, s[16:17] offset:3072
	global_load_dwordx4 v[128:131], v172, s[14:15]
	global_load_dwordx4 v[132:135], v172, s[14:15] offset:1024
	global_load_dwordx4 v[136:139], v172, s[14:15] offset:2048
	global_load_dwordx4 v[140:143], v172, s[14:15] offset:3072
	s_add_u32 s16, s16, 0x6000
	s_addc_u32 s17, s17, 0
	s_add_u32 s14, s14, 0x6000
	s_addc_u32 s15, s15, 0
	s_nop 1
	v_add_f32_dpp v144, v144, v144 quad_perm:[1,0,3,2] row_mask:0xf bank_mask:0xf bound_ctrl:1
	s_nop 1
	v_add_f32_dpp v144, v144, v144 quad_perm:[2,3,0,1] row_mask:0xf bank_mask:0xf bound_ctrl:1
	s_nop 1
	v_add_f32_dpp v144, v144, v144 row_half_mirror row_mask:0xf bank_mask:0xf bound_ctrl:1
	s_nop 1
	v_add_f32_dpp v144, v144, v144 row_mirror row_mask:0xf bank_mask:0xf bound_ctrl:1
	s_nop 1
	ds_bpermute_b32 v145, v174, v144
	s_waitcnt lgkmcnt(0)
	v_add_f32_e32 v144, v144, v145
	ds_bpermute_b32 v145, v175, v144
	s_waitcnt lgkmcnt(0)
	v_add_f32_e32 v144, v144, v145
	v_mov_b32_e32 v145, 0x358637bd
	v_fmac_f32_e32 v145, 0x3a800000, v144
	v_rsq_f32_e32 v146, v145
	s_nop 0
	s_waitcnt vmcnt(24)
	s_waitcnt vmcnt(16)
	v_add_f32_e32 v80, 1.0, v80
	v_add_f32_e32 v81, 1.0, v81
	v_add_f32_e32 v82, 1.0, v82
	v_add_f32_e32 v83, 1.0, v83
	v_add_f32_e32 v84, 1.0, v84
	v_add_f32_e32 v85, 1.0, v85
	v_add_f32_e32 v86, 1.0, v86
	v_add_f32_e32 v87, 1.0, v87
	v_add_f32_e32 v88, 1.0, v88
	v_add_f32_e32 v89, 1.0, v89
	v_add_f32_e32 v90, 1.0, v90
	v_add_f32_e32 v91, 1.0, v91
	v_add_f32_e32 v92, 1.0, v92
	v_add_f32_e32 v93, 1.0, v93
	v_add_f32_e32 v94, 1.0, v94
	v_add_f32_e32 v95, 1.0, v95
	v_mul_f32_e32 v156, v0, v146
	v_mul_f32_e32 v157, v1, v146
	v_mul_f32_e32 v158, v2, v146
	v_mul_f32_e32 v159, v3, v146
	v_mul_f32_e32 v160, v4, v146
	v_mul_f32_e32 v161, v5, v146
	v_mul_f32_e32 v162, v6, v146
	v_mul_f32_e32 v163, v7, v146
	v_mul_f32_e32 v164, v8, v146
	v_mul_f32_e32 v165, v9, v146
	v_mul_f32_e32 v166, v10, v146
	v_mul_f32_e32 v167, v11, v146
	v_mul_f32_e32 v168, v12, v146
	v_mul_f32_e32 v169, v13, v146
	v_mul_f32_e32 v170, v14, v146
	v_mul_f32_e32 v171, v15, v146
	v_mul_f32_e32 v156, v64, v156
	v_mul_f32_e32 v157, v65, v157
	v_mul_f32_e32 v158, v66, v158
	v_mul_f32_e32 v159, v67, v159
	v_mul_f32_e32 v160, v68, v160
	v_mul_f32_e32 v161, v69, v161
	v_mul_f32_e32 v162, v70, v162
	v_mul_f32_e32 v163, v71, v163
	v_mul_f32_e32 v164, v72, v164
	v_mul_f32_e32 v165, v73, v165
	v_mul_f32_e32 v166, v74, v166
	v_mul_f32_e32 v167, v75, v167
	v_mul_f32_e32 v168, v76, v168
	v_mul_f32_e32 v169, v77, v169
	v_mul_f32_e32 v170, v78, v170
	v_mul_f32_e32 v171, v79, v171
	v_fma_f32 v156, v80, v156, v112
	v_fma_f32 v157, v81, v157, v113
	v_fma_f32 v158, v82, v158, v114
	v_fma_f32 v159, v83, v159, v115
	v_fma_f32 v160, v84, v160, v116
	v_fma_f32 v161, v85, v161, v117
	v_fma_f32 v162, v86, v162, v118
	v_fma_f32 v163, v87, v163, v119
	v_fma_f32 v164, v88, v164, v120
	v_fma_f32 v165, v89, v165, v121
	v_fma_f32 v166, v90, v166, v122
	v_fma_f32 v167, v91, v167, v123
	v_fma_f32 v168, v92, v168, v124
	v_fma_f32 v169, v93, v169, v125
	v_fma_f32 v170, v94, v170, v126
	v_fma_f32 v171, v95, v171, v127
	global_load_dwordx4 v[0:3], v172, s[10:11]
	global_load_dwordx4 v[4:7], v172, s[10:11] offset:1024
	global_load_dwordx4 v[8:11], v172, s[10:11] offset:2048
	global_load_dwordx4 v[12:15], v172, s[10:11] offset:3072
	s_add_u32 s10, s10, 0x800000
	s_addc_u32 s11, s11, 0
	v_cvt_pk_bf16_f32 v148, v156, v157
	v_cvt_pk_bf16_f32 v149, v158, v159
	v_cvt_pk_bf16_f32 v150, v160, v161
	v_cvt_pk_bf16_f32 v151, v162, v163
	v_cvt_pk_bf16_f32 v152, v164, v165
	v_cvt_pk_bf16_f32 v153, v166, v167
	v_cvt_pk_bf16_f32 v154, v168, v169
	v_cvt_pk_bf16_f32 v155, v170, v171
	v_cndmask_b32_e32 v188, v150, v148, vcc
	v_cndmask_b32_e32 v189, v151, v149, vcc
	s_nop 1
	v_mov_b32_dpp v190, v188 quad_perm:[1,0,3,2] row_mask:0xf bank_mask:0xf
	v_mov_b32_dpp v191, v189 quad_perm:[1,0,3,2] row_mask:0xf bank_mask:0xf
	v_cndmask_b32_e32 v180, v148, v190, vcc
	v_cndmask_b32_e32 v181, v149, v191, vcc
	v_cndmask_b32_e32 v182, v190, v150, vcc
	v_cndmask_b32_e32 v183, v191, v151, vcc
	global_store_dwordx4 v177, v[180:183], s[12:13] sc1
	v_cndmask_b32_e32 v188, v154, v152, vcc
	v_cndmask_b32_e32 v189, v155, v153, vcc
	s_nop 1
	v_mov_b32_dpp v190, v188 quad_perm:[1,0,3,2] row_mask:0xf bank_mask:0xf
	v_mov_b32_dpp v191, v189 quad_perm:[1,0,3,2] row_mask:0xf bank_mask:0xf
	v_cndmask_b32_e32 v184, v152, v190, vcc
	v_cndmask_b32_e32 v185, v153, v191, vcc
	v_cndmask_b32_e32 v186, v190, v154, vcc
	v_cndmask_b32_e32 v187, v191, v155, vcc
	global_store_dwordx4 v177, v[184:187], s[12:13] offset:1024 sc1
	s_add_u32 s12, s12, 0x400000
	s_addc_u32 s13, s13, 0
	v_mul_f32_e32 v156, v16, v16
	v_mul_f32_e32 v157, v20, v20
	v_mul_f32_e32 v158, v24, v24
	v_mul_f32_e32 v159, v28, v28
	v_fmac_f32_e32 v156, v17, v17
	v_fmac_f32_e32 v157, v21, v21
	v_fmac_f32_e32 v158, v25, v25
	v_fmac_f32_e32 v159, v29, v29
	v_fmac_f32_e32 v156, v18, v18
	v_fmac_f32_e32 v157, v22, v22
	v_fmac_f32_e32 v158, v26, v26
	v_fmac_f32_e32 v159, v30, v30
	v_fmac_f32_e32 v156, v19, v19
	v_fmac_f32_e32 v157, v23, v23
	v_fmac_f32_e32 v158, v27, v27
	v_fmac_f32_e32 v159, v31, v31
	v_add_f32_e32 v156, v156, v157
	v_add_f32_e32 v158, v158, v159
	v_add_f32_e32 v144, v156, v158
	global_load_dwordx4 v[80:83], v172, s[16:17]
	global_load_dwordx4 v[84:87], v172, s[16:17] offset:1024
	global_load_dwordx4 v[88:91], v172, s[16:17] offset:2048
	global_load_dwordx4 v[92:95], v172, s[16:17] offset:3072
	global_load_dwordx4 v[112:115], v172, s[14:15]
	global_load_dwordx4 v[116:119], v172, s[14:15] offset:1024
	global_load_dwordx4 v[120:123], v172, s[14:15] offset:2048
	global_load_dwordx4 v[124:127], v172, s[14:15] offset:3072
	s_add_u32 s16, s16, 0x6000
	s_addc_u32 s17, s17, 0
	s_add_u32 s14, s14, 0x6000
	s_addc_u32 s15, s15, 0
	s_nop 1
	v_add_f32_dpp v144, v144, v144 quad_perm:[1,0,3,2] row_mask:0xf bank_mask:0xf bound_ctrl:1
	s_nop 1
	v_add_f32_dpp v144, v144, v144 quad_perm:[2,3,0,1] row_mask:0xf bank_mask:0xf bound_ctrl:1
	s_nop 1
	v_add_f32_dpp v144, v144, v144 row_half_mirror row_mask:0xf bank_mask:0xf bound_ctrl:1
	s_nop 1
	v_add_f32_dpp v144, v144, v144 row_mirror row_mask:0xf bank_mask:0xf bound_ctrl:1
	s_nop 1
	ds_bpermute_b32 v145, v174, v144
	s_waitcnt lgkmcnt(0)
	v_add_f32_e32 v144, v144, v145
	ds_bpermute_b32 v145, v175, v144
	s_waitcnt lgkmcnt(0)
	v_add_f32_e32 v144, v144, v145
	v_mov_b32_e32 v145, 0x358637bd
	v_fmac_f32_e32 v145, 0x3a800000, v144
	v_rsq_f32_e32 v146, v145
	s_nop 0
	s_waitcnt vmcnt(14)
	v_add_f32_e32 v96, 1.0, v96
	v_add_f32_e32 v97, 1.0, v97
	v_add_f32_e32 v98, 1.0, v98
	v_add_f32_e32 v99, 1.0, v99
	v_add_f32_e32 v100, 1.0, v100
	v_add_f32_e32 v101, 1.0, v101
	v_add_f32_e32 v102, 1.0, v102
	v_add_f32_e32 v103, 1.0, v103
	v_add_f32_e32 v104, 1.0, v104
	v_add_f32_e32 v105, 1.0, v105
	v_add_f32_e32 v106, 1.0, v106
	v_add_f32_e32 v107, 1.0, v107
	v_add_f32_e32 v108, 1.0, v108
	v_add_f32_e32 v109, 1.0, v109
	v_add_f32_e32 v110, 1.0, v110
	v_add_f32_e32 v111, 1.0, v111
	v_mul_f32_e32 v156, v16, v146
	v_mul_f32_e32 v157, v17, v146
	v_mul_f32_e32 v158, v18, v146
	v_mul_f32_e32 v159, v19, v146
	v_mul_f32_e32 v160, v20, v146
	v_mul_f32_e32 v161, v21, v146
	v_mul_f32_e32 v162, v22, v146
	v_mul_f32_e32 v163, v23, v146
	v_mul_f32_e32 v164, v24, v146
	v_mul_f32_e32 v165, v25, v146
	v_mul_f32_e32 v166, v26, v146
	v_mul_f32_e32 v167, v27, v146
	v_mul_f32_e32 v168, v28, v146
	v_mul_f32_e32 v169, v29, v146
	v_mul_f32_e32 v170, v30, v146
	v_mul_f32_e32 v171, v31, v146
	v_mul_f32_e32 v156, v64, v156
	v_mul_f32_e32 v157, v65, v157
	v_mul_f32_e32 v158, v66, v158
	v_mul_f32_e32 v159, v67, v159
	v_mul_f32_e32 v160, v68, v160
	v_mul_f32_e32 v161, v69, v161
	v_mul_f32_e32 v162, v70, v162
	v_mul_f32_e32 v163, v71, v163
	v_mul_f32_e32 v164, v72, v164
	v_mul_f32_e32 v165, v73, v165
	v_mul_f32_e32 v166, v74, v166
	v_mul_f32_e32 v167, v75, v167
	v_mul_f32_e32 v168, v76, v168
	v_mul_f32_e32 v169, v77, v169
	v_mul_f32_e32 v170, v78, v170
	v_mul_f32_e32 v171, v79, v171
	v_fma_f32 v156, v96, v156, v128
	v_fma_f32 v157, v97, v157, v129
	v_fma_f32 v158, v98, v158, v130
	v_fma_f32 v159, v99, v159, v131
	v_fma_f32 v160, v100, v160, v132
	v_fma_f32 v161, v101, v161, v133
	v_fma_f32 v162, v102, v162, v134
	v_fma_f32 v163, v103, v163, v135
	v_fma_f32 v164, v104, v164, v136
	v_fma_f32 v165, v105, v165, v137
	v_fma_f32 v166, v106, v166, v138
	v_fma_f32 v167, v107, v167, v139
	v_fma_f32 v168, v108, v168, v140
	v_fma_f32 v169, v109, v169, v141
	v_fma_f32 v170, v110, v170, v142
	v_fma_f32 v171, v111, v171, v143
	global_load_dwordx4 v[16:19], v172, s[10:11]
	global_load_dwordx4 v[20:23], v172, s[10:11] offset:1024
	global_load_dwordx4 v[24:27], v172, s[10:11] offset:2048
	global_load_dwordx4 v[28:31], v172, s[10:11] offset:3072
	s_add_u32 s10, s10, 0x800000
	s_addc_u32 s11, s11, 0
	v_cvt_pk_bf16_f32 v148, v156, v157
	v_cvt_pk_bf16_f32 v149, v158, v159
	v_cvt_pk_bf16_f32 v150, v160, v161
	v_cvt_pk_bf16_f32 v151, v162, v163
	v_cvt_pk_bf16_f32 v152, v164, v165
	v_cvt_pk_bf16_f32 v153, v166, v167
	v_cvt_pk_bf16_f32 v154, v168, v169
	v_cvt_pk_bf16_f32 v155, v170, v171
	v_cndmask_b32_e32 v188, v150, v148, vcc
	v_cndmask_b32_e32 v189, v151, v149, vcc
	s_nop 1
	v_mov_b32_dpp v190, v188 quad_perm:[1,0,3,2] row_mask:0xf bank_mask:0xf
	v_mov_b32_dpp v191, v189 quad_perm:[1,0,3,2] row_mask:0xf bank_mask:0xf
	v_cndmask_b32_e32 v180, v148, v190, vcc
	v_cndmask_b32_e32 v181, v149, v191, vcc
	v_cndmask_b32_e32 v182, v190, v150, vcc
	v_cndmask_b32_e32 v183, v191, v151, vcc
	global_store_dwordx4 v177, v[180:183], s[12:13] sc1
	v_cndmask_b32_e32 v188, v154, v152, vcc
	v_cndmask_b32_e32 v189, v155, v153, vcc
	s_nop 1
	v_mov_b32_dpp v190, v188 quad_perm:[1,0,3,2] row_mask:0xf bank_mask:0xf
	v_mov_b32_dpp v191, v189 quad_perm:[1,0,3,2] row_mask:0xf bank_mask:0xf
	v_cndmask_b32_e32 v184, v152, v190, vcc
	v_cndmask_b32_e32 v185, v153, v191, vcc
	v_cndmask_b32_e32 v186, v190, v154, vcc
	v_cndmask_b32_e32 v187, v191, v155, vcc
	global_store_dwordx4 v177, v[184:187], s[12:13] offset:1024 sc1
	s_add_u32 s12, s12, 0x400000
	s_addc_u32 s13, s13, 0
	v_mul_f32_e32 v156, v32, v32
	v_mul_f32_e32 v157, v36, v36
	v_mul_f32_e32 v158, v40, v40
	v_mul_f32_e32 v159, v44, v44
	v_fmac_f32_e32 v156, v33, v33
	v_fmac_f32_e32 v157, v37, v37
	v_fmac_f32_e32 v158, v41, v41
	v_fmac_f32_e32 v159, v45, v45
	v_fmac_f32_e32 v156, v34, v34
	v_fmac_f32_e32 v157, v38, v38
	v_fmac_f32_e32 v158, v42, v42
	v_fmac_f32_e32 v159, v46, v46
	v_fmac_f32_e32 v156, v35, v35
	v_fmac_f32_e32 v157, v39, v39
	v_fmac_f32_e32 v158, v43, v43
	v_fmac_f32_e32 v159, v47, v47
	v_add_f32_e32 v156, v156, v157
	v_add_f32_e32 v158, v158, v159
	v_add_f32_e32 v144, v156, v158
	global_load_dwordx4 v[96:99], v172, s[16:17]
	global_load_dwordx4 v[100:103], v172, s[16:17] offset:1024
	global_load_dwordx4 v[104:107], v172, s[16:17] offset:2048
	global_load_dwordx4 v[108:111], v172, s[16:17] offset:3072
	global_load_dwordx4 v[128:131], v172, s[14:15]
	global_load_dwordx4 v[132:135], v172, s[14:15] offset:1024
	global_load_dwordx4 v[136:139], v172, s[14:15] offset:2048
	global_load_dwordx4 v[140:143], v172, s[14:15] offset:3072
	s_add_u32 s16, s16, 0x6000
	s_addc_u32 s17, s17, 0
	s_add_u32 s14, s14, 0x6000
	s_addc_u32 s15, s15, 0
	s_nop 1
	v_add_f32_dpp v144, v144, v144 quad_perm:[1,0,3,2] row_mask:0xf bank_mask:0xf bound_ctrl:1
	s_nop 1
	v_add_f32_dpp v144, v144, v144 quad_perm:[2,3,0,1] row_mask:0xf bank_mask:0xf bound_ctrl:1
	s_nop 1
	v_add_f32_dpp v144, v144, v144 row_half_mirror row_mask:0xf bank_mask:0xf bound_ctrl:1
	s_nop 1
	v_add_f32_dpp v144, v144, v144 row_mirror row_mask:0xf bank_mask:0xf bound_ctrl:1
	s_nop 1
	ds_bpermute_b32 v145, v174, v144
	s_waitcnt lgkmcnt(0)
	v_add_f32_e32 v144, v144, v145
	ds_bpermute_b32 v145, v175, v144
	s_waitcnt lgkmcnt(0)
	v_add_f32_e32 v144, v144, v145
	v_mov_b32_e32 v145, 0x358637bd
	v_fmac_f32_e32 v145, 0x3a800000, v144
	v_rsq_f32_e32 v146, v145
	s_nop 0
	s_waitcnt vmcnt(14)
	v_add_f32_e32 v80, 1.0, v80
	v_add_f32_e32 v81, 1.0, v81
	v_add_f32_e32 v82, 1.0, v82
	v_add_f32_e32 v83, 1.0, v83
	v_add_f32_e32 v84, 1.0, v84
	v_add_f32_e32 v85, 1.0, v85
	v_add_f32_e32 v86, 1.0, v86
	v_add_f32_e32 v87, 1.0, v87
	v_add_f32_e32 v88, 1.0, v88
	v_add_f32_e32 v89, 1.0, v89
	v_add_f32_e32 v90, 1.0, v90
	v_add_f32_e32 v91, 1.0, v91
	v_add_f32_e32 v92, 1.0, v92
	v_add_f32_e32 v93, 1.0, v93
	v_add_f32_e32 v94, 1.0, v94
	v_add_f32_e32 v95, 1.0, v95
	v_mul_f32_e32 v156, v32, v146
	v_mul_f32_e32 v157, v33, v146
	v_mul_f32_e32 v158, v34, v146
	v_mul_f32_e32 v159, v35, v146
	v_mul_f32_e32 v160, v36, v146
	v_mul_f32_e32 v161, v37, v146
	v_mul_f32_e32 v162, v38, v146
	v_mul_f32_e32 v163, v39, v146
	v_mul_f32_e32 v164, v40, v146
	v_mul_f32_e32 v165, v41, v146
	v_mul_f32_e32 v166, v42, v146
	v_mul_f32_e32 v167, v43, v146
	v_mul_f32_e32 v168, v44, v146
	v_mul_f32_e32 v169, v45, v146
	v_mul_f32_e32 v170, v46, v146
	v_mul_f32_e32 v171, v47, v146
	v_mul_f32_e32 v156, v64, v156
	v_mul_f32_e32 v157, v65, v157
	v_mul_f32_e32 v158, v66, v158
	v_mul_f32_e32 v159, v67, v159
	v_mul_f32_e32 v160, v68, v160
	v_mul_f32_e32 v161, v69, v161
	v_mul_f32_e32 v162, v70, v162
	v_mul_f32_e32 v163, v71, v163
	v_mul_f32_e32 v164, v72, v164
	v_mul_f32_e32 v165, v73, v165
	v_mul_f32_e32 v166, v74, v166
	v_mul_f32_e32 v167, v75, v167
	v_mul_f32_e32 v168, v76, v168
	v_mul_f32_e32 v169, v77, v169
	v_mul_f32_e32 v170, v78, v170
	v_mul_f32_e32 v171, v79, v171
	v_fma_f32 v156, v80, v156, v112
	v_fma_f32 v157, v81, v157, v113
	v_fma_f32 v158, v82, v158, v114
	v_fma_f32 v159, v83, v159, v115
	v_fma_f32 v160, v84, v160, v116
	v_fma_f32 v161, v85, v161, v117
	v_fma_f32 v162, v86, v162, v118
	v_fma_f32 v163, v87, v163, v119
	v_fma_f32 v164, v88, v164, v120
	v_fma_f32 v165, v89, v165, v121
	v_fma_f32 v166, v90, v166, v122
	v_fma_f32 v167, v91, v167, v123
	v_fma_f32 v168, v92, v168, v124
	v_fma_f32 v169, v93, v169, v125
	v_fma_f32 v170, v94, v170, v126
	v_fma_f32 v171, v95, v171, v127
	global_load_dwordx4 v[32:35], v172, s[10:11]
	global_load_dwordx4 v[36:39], v172, s[10:11] offset:1024
	global_load_dwordx4 v[40:43], v172, s[10:11] offset:2048
	global_load_dwordx4 v[44:47], v172, s[10:11] offset:3072
	s_add_u32 s10, s10, 0x800000
	s_addc_u32 s11, s11, 0
	v_cvt_pk_bf16_f32 v148, v156, v157
	v_cvt_pk_bf16_f32 v149, v158, v159
	v_cvt_pk_bf16_f32 v150, v160, v161
	v_cvt_pk_bf16_f32 v151, v162, v163
	v_cvt_pk_bf16_f32 v152, v164, v165
	v_cvt_pk_bf16_f32 v153, v166, v167
	v_cvt_pk_bf16_f32 v154, v168, v169
	v_cvt_pk_bf16_f32 v155, v170, v171
	v_cndmask_b32_e32 v188, v150, v148, vcc
	v_cndmask_b32_e32 v189, v151, v149, vcc
	s_nop 1
	v_mov_b32_dpp v190, v188 quad_perm:[1,0,3,2] row_mask:0xf bank_mask:0xf
	v_mov_b32_dpp v191, v189 quad_perm:[1,0,3,2] row_mask:0xf bank_mask:0xf
	v_cndmask_b32_e32 v180, v148, v190, vcc
	v_cndmask_b32_e32 v181, v149, v191, vcc
	v_cndmask_b32_e32 v182, v190, v150, vcc
	v_cndmask_b32_e32 v183, v191, v151, vcc
	global_store_dwordx4 v177, v[180:183], s[12:13] sc1
	v_cndmask_b32_e32 v188, v154, v152, vcc
	v_cndmask_b32_e32 v189, v155, v153, vcc
	s_nop 1
	v_mov_b32_dpp v190, v188 quad_perm:[1,0,3,2] row_mask:0xf bank_mask:0xf
	v_mov_b32_dpp v191, v189 quad_perm:[1,0,3,2] row_mask:0xf bank_mask:0xf
	v_cndmask_b32_e32 v184, v152, v190, vcc
	v_cndmask_b32_e32 v185, v153, v191, vcc
	v_cndmask_b32_e32 v186, v190, v154, vcc
	v_cndmask_b32_e32 v187, v191, v155, vcc
	global_store_dwordx4 v177, v[184:187], s[12:13] offset:1024 sc1
	s_add_u32 s12, s12, 0x400000
	s_addc_u32 s13, s13, 0
	v_mul_f32_e32 v156, v48, v48
	v_mul_f32_e32 v157, v52, v52
	v_mul_f32_e32 v158, v56, v56
	v_mul_f32_e32 v159, v60, v60
	v_fmac_f32_e32 v156, v49, v49
	v_fmac_f32_e32 v157, v53, v53
	v_fmac_f32_e32 v158, v57, v57
	v_fmac_f32_e32 v159, v61, v61
	v_fmac_f32_e32 v156, v50, v50
	v_fmac_f32_e32 v157, v54, v54
	v_fmac_f32_e32 v158, v58, v58
	v_fmac_f32_e32 v159, v62, v62
	v_fmac_f32_e32 v156, v51, v51
	v_fmac_f32_e32 v157, v55, v55
	v_fmac_f32_e32 v158, v59, v59
	v_fmac_f32_e32 v159, v63, v63
	v_add_f32_e32 v156, v156, v157
	v_add_f32_e32 v158, v158, v159
	v_add_f32_e32 v144, v156, v158
	global_load_dwordx4 v[80:83], v172, s[16:17]
	global_load_dwordx4 v[84:87], v172, s[16:17] offset:1024
	global_load_dwordx4 v[88:91], v172, s[16:17] offset:2048
	global_load_dwordx4 v[92:95], v172, s[16:17] offset:3072
	global_load_dwordx4 v[112:115], v172, s[14:15]
	global_load_dwordx4 v[116:119], v172, s[14:15] offset:1024
	global_load_dwordx4 v[120:123], v172, s[14:15] offset:2048
	global_load_dwordx4 v[124:127], v172, s[14:15] offset:3072
	s_add_u32 s16, s16, 0x6000
	s_addc_u32 s17, s17, 0
	s_add_u32 s14, s14, 0x6000
	s_addc_u32 s15, s15, 0
	s_nop 1
	v_add_f32_dpp v144, v144, v144 quad_perm:[1,0,3,2] row_mask:0xf bank_mask:0xf bound_ctrl:1
	s_nop 1
	v_add_f32_dpp v144, v144, v144 quad_perm:[2,3,0,1] row_mask:0xf bank_mask:0xf bound_ctrl:1
	s_nop 1
	v_add_f32_dpp v144, v144, v144 row_half_mirror row_mask:0xf bank_mask:0xf bound_ctrl:1
	s_nop 1
	v_add_f32_dpp v144, v144, v144 row_mirror row_mask:0xf bank_mask:0xf bound_ctrl:1
	s_nop 1
	ds_bpermute_b32 v145, v174, v144
	s_waitcnt lgkmcnt(0)
	v_add_f32_e32 v144, v144, v145
	ds_bpermute_b32 v145, v175, v144
	s_waitcnt lgkmcnt(0)
	v_add_f32_e32 v144, v144, v145
	v_mov_b32_e32 v145, 0x358637bd
	v_fmac_f32_e32 v145, 0x3a800000, v144
	v_rsq_f32_e32 v146, v145
	s_nop 0
	s_waitcnt vmcnt(14)
	v_add_f32_e32 v96, 1.0, v96
	v_add_f32_e32 v97, 1.0, v97
	v_add_f32_e32 v98, 1.0, v98
	v_add_f32_e32 v99, 1.0, v99
	v_add_f32_e32 v100, 1.0, v100
	v_add_f32_e32 v101, 1.0, v101
	v_add_f32_e32 v102, 1.0, v102
	v_add_f32_e32 v103, 1.0, v103
	v_add_f32_e32 v104, 1.0, v104
	v_add_f32_e32 v105, 1.0, v105
	v_add_f32_e32 v106, 1.0, v106
	v_add_f32_e32 v107, 1.0, v107
	v_add_f32_e32 v108, 1.0, v108
	v_add_f32_e32 v109, 1.0, v109
	v_add_f32_e32 v110, 1.0, v110
	v_add_f32_e32 v111, 1.0, v111
	v_mul_f32_e32 v156, v48, v146
	v_mul_f32_e32 v157, v49, v146
	v_mul_f32_e32 v158, v50, v146
	v_mul_f32_e32 v159, v51, v146
	v_mul_f32_e32 v160, v52, v146
	v_mul_f32_e32 v161, v53, v146
	v_mul_f32_e32 v162, v54, v146
	v_mul_f32_e32 v163, v55, v146
	v_mul_f32_e32 v164, v56, v146
	v_mul_f32_e32 v165, v57, v146
	v_mul_f32_e32 v166, v58, v146
	v_mul_f32_e32 v167, v59, v146
	v_mul_f32_e32 v168, v60, v146
	v_mul_f32_e32 v169, v61, v146
	v_mul_f32_e32 v170, v62, v146
	v_mul_f32_e32 v171, v63, v146
	v_mul_f32_e32 v156, v64, v156
	v_mul_f32_e32 v157, v65, v157
	v_mul_f32_e32 v158, v66, v158
	v_mul_f32_e32 v159, v67, v159
	v_mul_f32_e32 v160, v68, v160
	v_mul_f32_e32 v161, v69, v161
	v_mul_f32_e32 v162, v70, v162
	v_mul_f32_e32 v163, v71, v163
	v_mul_f32_e32 v164, v72, v164
	v_mul_f32_e32 v165, v73, v165
	v_mul_f32_e32 v166, v74, v166
	v_mul_f32_e32 v167, v75, v167
	v_mul_f32_e32 v168, v76, v168
	v_mul_f32_e32 v169, v77, v169
	v_mul_f32_e32 v170, v78, v170
	v_mul_f32_e32 v171, v79, v171
	v_fma_f32 v156, v96, v156, v128
	v_fma_f32 v157, v97, v157, v129
	v_fma_f32 v158, v98, v158, v130
	v_fma_f32 v159, v99, v159, v131
	v_fma_f32 v160, v100, v160, v132
	v_fma_f32 v161, v101, v161, v133
	v_fma_f32 v162, v102, v162, v134
	v_fma_f32 v163, v103, v163, v135
	v_fma_f32 v164, v104, v164, v136
	v_fma_f32 v165, v105, v165, v137
	v_fma_f32 v166, v106, v166, v138
	v_fma_f32 v167, v107, v167, v139
	v_fma_f32 v168, v108, v168, v140
	v_fma_f32 v169, v109, v169, v141
	v_fma_f32 v170, v110, v170, v142
	v_fma_f32 v171, v111, v171, v143
	global_load_dwordx4 v[48:51], v172, s[10:11]
	global_load_dwordx4 v[52:55], v172, s[10:11] offset:1024
	global_load_dwordx4 v[56:59], v172, s[10:11] offset:2048
	global_load_dwordx4 v[60:63], v172, s[10:11] offset:3072
	s_add_u32 s10, s10, 0x800000
	s_addc_u32 s11, s11, 0
	v_cvt_pk_bf16_f32 v148, v156, v157
	v_cvt_pk_bf16_f32 v149, v158, v159
	v_cvt_pk_bf16_f32 v150, v160, v161
	v_cvt_pk_bf16_f32 v151, v162, v163
	v_cvt_pk_bf16_f32 v152, v164, v165
	v_cvt_pk_bf16_f32 v153, v166, v167
	v_cvt_pk_bf16_f32 v154, v168, v169
	v_cvt_pk_bf16_f32 v155, v170, v171
	v_cndmask_b32_e32 v188, v150, v148, vcc
	v_cndmask_b32_e32 v189, v151, v149, vcc
	s_nop 1
	v_mov_b32_dpp v190, v188 quad_perm:[1,0,3,2] row_mask:0xf bank_mask:0xf
	v_mov_b32_dpp v191, v189 quad_perm:[1,0,3,2] row_mask:0xf bank_mask:0xf
	v_cndmask_b32_e32 v180, v148, v190, vcc
	v_cndmask_b32_e32 v181, v149, v191, vcc
	v_cndmask_b32_e32 v182, v190, v150, vcc
	v_cndmask_b32_e32 v183, v191, v151, vcc
	global_store_dwordx4 v177, v[180:183], s[12:13] sc1
	v_cndmask_b32_e32 v188, v154, v152, vcc
	v_cndmask_b32_e32 v189, v155, v153, vcc
	s_nop 1
	v_mov_b32_dpp v190, v188 quad_perm:[1,0,3,2] row_mask:0xf bank_mask:0xf
	v_mov_b32_dpp v191, v189 quad_perm:[1,0,3,2] row_mask:0xf bank_mask:0xf
	v_cndmask_b32_e32 v184, v152, v190, vcc
	v_cndmask_b32_e32 v185, v153, v191, vcc
	v_cndmask_b32_e32 v186, v190, v154, vcc
	v_cndmask_b32_e32 v187, v191, v155, vcc
	global_store_dwordx4 v177, v[184:187], s[12:13] offset:1024 sc1
	s_add_u32 s12, s12, 0x400000
	s_addc_u32 s13, s13, 0
	v_mul_f32_e32 v156, v0, v0
	v_mul_f32_e32 v157, v4, v4
	v_mul_f32_e32 v158, v8, v8
	v_mul_f32_e32 v159, v12, v12
	v_fmac_f32_e32 v156, v1, v1
	v_fmac_f32_e32 v157, v5, v5
	v_fmac_f32_e32 v158, v9, v9
	v_fmac_f32_e32 v159, v13, v13
	v_fmac_f32_e32 v156, v2, v2
	v_fmac_f32_e32 v157, v6, v6
	v_fmac_f32_e32 v158, v10, v10
	v_fmac_f32_e32 v159, v14, v14
	v_fmac_f32_e32 v156, v3, v3
	v_fmac_f32_e32 v157, v7, v7
	v_fmac_f32_e32 v158, v11, v11
	v_fmac_f32_e32 v159, v15, v15
	v_add_f32_e32 v156, v156, v157
	v_add_f32_e32 v158, v158, v159
	v_add_f32_e32 v144, v156, v158
	global_load_dwordx4 v[96:99], v172, s[16:17]
	global_load_dwordx4 v[100:103], v172, s[16:17] offset:1024
	global_load_dwordx4 v[104:107], v172, s[16:17] offset:2048
	global_load_dwordx4 v[108:111], v172, s[16:17] offset:3072
	global_load_dwordx4 v[128:131], v172, s[14:15]
	global_load_dwordx4 v[132:135], v172, s[14:15] offset:1024
	global_load_dwordx4 v[136:139], v172, s[14:15] offset:2048
	global_load_dwordx4 v[140:143], v172, s[14:15] offset:3072
	s_add_u32 s16, s16, 0x6000
	s_addc_u32 s17, s17, 0
	s_add_u32 s14, s14, 0x6000
	s_addc_u32 s15, s15, 0
	s_nop 1
	v_add_f32_dpp v144, v144, v144 quad_perm:[1,0,3,2] row_mask:0xf bank_mask:0xf bound_ctrl:1
	s_nop 1
	v_add_f32_dpp v144, v144, v144 quad_perm:[2,3,0,1] row_mask:0xf bank_mask:0xf bound_ctrl:1
	s_nop 1
	v_add_f32_dpp v144, v144, v144 row_half_mirror row_mask:0xf bank_mask:0xf bound_ctrl:1
	s_nop 1
	v_add_f32_dpp v144, v144, v144 row_mirror row_mask:0xf bank_mask:0xf bound_ctrl:1
	s_nop 1
	ds_bpermute_b32 v145, v174, v144
	s_waitcnt lgkmcnt(0)
	v_add_f32_e32 v144, v144, v145
	ds_bpermute_b32 v145, v175, v144
	s_waitcnt lgkmcnt(0)
	v_add_f32_e32 v144, v144, v145
	v_mov_b32_e32 v145, 0x358637bd
	v_fmac_f32_e32 v145, 0x3a800000, v144
	v_rsq_f32_e32 v146, v145
	s_nop 0
	s_waitcnt vmcnt(14)
	v_add_f32_e32 v80, 1.0, v80
	v_add_f32_e32 v81, 1.0, v81
	v_add_f32_e32 v82, 1.0, v82
	v_add_f32_e32 v83, 1.0, v83
	v_add_f32_e32 v84, 1.0, v84
	v_add_f32_e32 v85, 1.0, v85
	v_add_f32_e32 v86, 1.0, v86
	v_add_f32_e32 v87, 1.0, v87
	v_add_f32_e32 v88, 1.0, v88
	v_add_f32_e32 v89, 1.0, v89
	v_add_f32_e32 v90, 1.0, v90
	v_add_f32_e32 v91, 1.0, v91
	v_add_f32_e32 v92, 1.0, v92
	v_add_f32_e32 v93, 1.0, v93
	v_add_f32_e32 v94, 1.0, v94
	v_add_f32_e32 v95, 1.0, v95
	v_mul_f32_e32 v156, v0, v146
	v_mul_f32_e32 v157, v1, v146
	v_mul_f32_e32 v158, v2, v146
	v_mul_f32_e32 v159, v3, v146
	v_mul_f32_e32 v160, v4, v146
	v_mul_f32_e32 v161, v5, v146
	v_mul_f32_e32 v162, v6, v146
	v_mul_f32_e32 v163, v7, v146
	v_mul_f32_e32 v164, v8, v146
	v_mul_f32_e32 v165, v9, v146
	v_mul_f32_e32 v166, v10, v146
	v_mul_f32_e32 v167, v11, v146
	v_mul_f32_e32 v168, v12, v146
	v_mul_f32_e32 v169, v13, v146
	v_mul_f32_e32 v170, v14, v146
	v_mul_f32_e32 v171, v15, v146
	v_mul_f32_e32 v156, v64, v156
	v_mul_f32_e32 v157, v65, v157
	v_mul_f32_e32 v158, v66, v158
	v_mul_f32_e32 v159, v67, v159
	v_mul_f32_e32 v160, v68, v160
	v_mul_f32_e32 v161, v69, v161
	v_mul_f32_e32 v162, v70, v162
	v_mul_f32_e32 v163, v71, v163
	v_mul_f32_e32 v164, v72, v164
	v_mul_f32_e32 v165, v73, v165
	v_mul_f32_e32 v166, v74, v166
	v_mul_f32_e32 v167, v75, v167
	v_mul_f32_e32 v168, v76, v168
	v_mul_f32_e32 v169, v77, v169
	v_mul_f32_e32 v170, v78, v170
	v_mul_f32_e32 v171, v79, v171
	v_fma_f32 v156, v80, v156, v112
	v_fma_f32 v157, v81, v157, v113
	v_fma_f32 v158, v82, v158, v114
	v_fma_f32 v159, v83, v159, v115
	v_fma_f32 v160, v84, v160, v116
	v_fma_f32 v161, v85, v161, v117
	v_fma_f32 v162, v86, v162, v118
	v_fma_f32 v163, v87, v163, v119
	v_fma_f32 v164, v88, v164, v120
	v_fma_f32 v165, v89, v165, v121
	v_fma_f32 v166, v90, v166, v122
	v_fma_f32 v167, v91, v167, v123
	v_fma_f32 v168, v92, v168, v124
	v_fma_f32 v169, v93, v169, v125
	v_fma_f32 v170, v94, v170, v126
	v_fma_f32 v171, v95, v171, v127
	v_cvt_pk_bf16_f32 v148, v156, v157
	v_cvt_pk_bf16_f32 v149, v158, v159
	v_cvt_pk_bf16_f32 v150, v160, v161
	v_cvt_pk_bf16_f32 v151, v162, v163
	v_cvt_pk_bf16_f32 v152, v164, v165
	v_cvt_pk_bf16_f32 v153, v166, v167
	v_cvt_pk_bf16_f32 v154, v168, v169
	v_cvt_pk_bf16_f32 v155, v170, v171
	v_cndmask_b32_e32 v188, v150, v148, vcc
	v_cndmask_b32_e32 v189, v151, v149, vcc
	s_nop 1
	v_mov_b32_dpp v190, v188 quad_perm:[1,0,3,2] row_mask:0xf bank_mask:0xf
	v_mov_b32_dpp v191, v189 quad_perm:[1,0,3,2] row_mask:0xf bank_mask:0xf
	v_cndmask_b32_e32 v180, v148, v190, vcc
	v_cndmask_b32_e32 v181, v149, v191, vcc
	v_cndmask_b32_e32 v182, v190, v150, vcc
	v_cndmask_b32_e32 v183, v191, v151, vcc
	global_store_dwordx4 v177, v[180:183], s[12:13] sc1
	v_cndmask_b32_e32 v188, v154, v152, vcc
	v_cndmask_b32_e32 v189, v155, v153, vcc
	s_nop 1
	v_mov_b32_dpp v190, v188 quad_perm:[1,0,3,2] row_mask:0xf bank_mask:0xf
	v_mov_b32_dpp v191, v189 quad_perm:[1,0,3,2] row_mask:0xf bank_mask:0xf
	v_cndmask_b32_e32 v184, v152, v190, vcc
	v_cndmask_b32_e32 v185, v153, v191, vcc
	v_cndmask_b32_e32 v186, v190, v154, vcc
	v_cndmask_b32_e32 v187, v191, v155, vcc
	global_store_dwordx4 v177, v[184:187], s[12:13] offset:1024 sc1
	s_add_u32 s12, s12, 0x400000
	s_addc_u32 s13, s13, 0
	v_mul_f32_e32 v156, v16, v16
	v_mul_f32_e32 v157, v20, v20
	v_mul_f32_e32 v158, v24, v24
	v_mul_f32_e32 v159, v28, v28
	v_fmac_f32_e32 v156, v17, v17
	v_fmac_f32_e32 v157, v21, v21
	v_fmac_f32_e32 v158, v25, v25
	v_fmac_f32_e32 v159, v29, v29
	v_fmac_f32_e32 v156, v18, v18
	v_fmac_f32_e32 v157, v22, v22
	v_fmac_f32_e32 v158, v26, v26
	v_fmac_f32_e32 v159, v30, v30
	v_fmac_f32_e32 v156, v19, v19
	v_fmac_f32_e32 v157, v23, v23
	v_fmac_f32_e32 v158, v27, v27
	v_fmac_f32_e32 v159, v31, v31
	v_add_f32_e32 v156, v156, v157
	v_add_f32_e32 v158, v158, v159
	v_add_f32_e32 v144, v156, v158
	global_load_dwordx4 v[80:83], v172, s[16:17]
	global_load_dwordx4 v[84:87], v172, s[16:17] offset:1024
	global_load_dwordx4 v[88:91], v172, s[16:17] offset:2048
	global_load_dwordx4 v[92:95], v172, s[16:17] offset:3072
	global_load_dwordx4 v[112:115], v172, s[14:15]
	global_load_dwordx4 v[116:119], v172, s[14:15] offset:1024
	global_load_dwordx4 v[120:123], v172, s[14:15] offset:2048
	global_load_dwordx4 v[124:127], v172, s[14:15] offset:3072
	s_add_u32 s16, s16, 0x6000
	s_addc_u32 s17, s17, 0
	s_add_u32 s14, s14, 0x6000
	s_addc_u32 s15, s15, 0
	s_nop 1
	v_add_f32_dpp v144, v144, v144 quad_perm:[1,0,3,2] row_mask:0xf bank_mask:0xf bound_ctrl:1
	s_nop 1
	v_add_f32_dpp v144, v144, v144 quad_perm:[2,3,0,1] row_mask:0xf bank_mask:0xf bound_ctrl:1
	s_nop 1
	v_add_f32_dpp v144, v144, v144 row_half_mirror row_mask:0xf bank_mask:0xf bound_ctrl:1
	s_nop 1
	v_add_f32_dpp v144, v144, v144 row_mirror row_mask:0xf bank_mask:0xf bound_ctrl:1
	s_nop 1
	ds_bpermute_b32 v145, v174, v144
	s_waitcnt lgkmcnt(0)
	v_add_f32_e32 v144, v144, v145
	ds_bpermute_b32 v145, v175, v144
	s_waitcnt lgkmcnt(0)
	v_add_f32_e32 v144, v144, v145
	v_mov_b32_e32 v145, 0x358637bd
	v_fmac_f32_e32 v145, 0x3a800000, v144
	v_rsq_f32_e32 v146, v145
	s_nop 0
	s_waitcnt vmcnt(10)
	v_add_f32_e32 v96, 1.0, v96
	v_add_f32_e32 v97, 1.0, v97
	v_add_f32_e32 v98, 1.0, v98
	v_add_f32_e32 v99, 1.0, v99
	v_add_f32_e32 v100, 1.0, v100
	v_add_f32_e32 v101, 1.0, v101
	v_add_f32_e32 v102, 1.0, v102
	v_add_f32_e32 v103, 1.0, v103
	v_add_f32_e32 v104, 1.0, v104
	v_add_f32_e32 v105, 1.0, v105
	v_add_f32_e32 v106, 1.0, v106
	v_add_f32_e32 v107, 1.0, v107
	v_add_f32_e32 v108, 1.0, v108
	v_add_f32_e32 v109, 1.0, v109
	v_add_f32_e32 v110, 1.0, v110
	v_add_f32_e32 v111, 1.0, v111
	v_mul_f32_e32 v156, v16, v146
	v_mul_f32_e32 v157, v17, v146
	v_mul_f32_e32 v158, v18, v146
	v_mul_f32_e32 v159, v19, v146
	v_mul_f32_e32 v160, v20, v146
	v_mul_f32_e32 v161, v21, v146
	v_mul_f32_e32 v162, v22, v146
	v_mul_f32_e32 v163, v23, v146
	v_mul_f32_e32 v164, v24, v146
	v_mul_f32_e32 v165, v25, v146
	v_mul_f32_e32 v166, v26, v146
	v_mul_f32_e32 v167, v27, v146
	v_mul_f32_e32 v168, v28, v146
	v_mul_f32_e32 v169, v29, v146
	v_mul_f32_e32 v170, v30, v146
	v_mul_f32_e32 v171, v31, v146
	v_mul_f32_e32 v156, v64, v156
	v_mul_f32_e32 v157, v65, v157
	v_mul_f32_e32 v158, v66, v158
	v_mul_f32_e32 v159, v67, v159
	v_mul_f32_e32 v160, v68, v160
	v_mul_f32_e32 v161, v69, v161
	v_mul_f32_e32 v162, v70, v162
	v_mul_f32_e32 v163, v71, v163
	v_mul_f32_e32 v164, v72, v164
	v_mul_f32_e32 v165, v73, v165
	v_mul_f32_e32 v166, v74, v166
	v_mul_f32_e32 v167, v75, v167
	v_mul_f32_e32 v168, v76, v168
	v_mul_f32_e32 v169, v77, v169
	v_mul_f32_e32 v170, v78, v170
	v_mul_f32_e32 v171, v79, v171
	v_fma_f32 v156, v96, v156, v128
	v_fma_f32 v157, v97, v157, v129
	v_fma_f32 v158, v98, v158, v130
	v_fma_f32 v159, v99, v159, v131
	v_fma_f32 v160, v100, v160, v132
	v_fma_f32 v161, v101, v161, v133
	v_fma_f32 v162, v102, v162, v134
	v_fma_f32 v163, v103, v163, v135
	v_fma_f32 v164, v104, v164, v136
	v_fma_f32 v165, v105, v165, v137
	v_fma_f32 v166, v106, v166, v138
	v_fma_f32 v167, v107, v167, v139
	v_fma_f32 v168, v108, v168, v140
	v_fma_f32 v169, v109, v169, v141
	v_fma_f32 v170, v110, v170, v142
	v_fma_f32 v171, v111, v171, v143
	v_cvt_pk_bf16_f32 v148, v156, v157
	v_cvt_pk_bf16_f32 v149, v158, v159
	v_cvt_pk_bf16_f32 v150, v160, v161
	v_cvt_pk_bf16_f32 v151, v162, v163
	v_cvt_pk_bf16_f32 v152, v164, v165
	v_cvt_pk_bf16_f32 v153, v166, v167
	v_cvt_pk_bf16_f32 v154, v168, v169
	v_cvt_pk_bf16_f32 v155, v170, v171
	v_cndmask_b32_e32 v188, v150, v148, vcc
	v_cndmask_b32_e32 v189, v151, v149, vcc
	s_nop 1
	v_mov_b32_dpp v190, v188 quad_perm:[1,0,3,2] row_mask:0xf bank_mask:0xf
	v_mov_b32_dpp v191, v189 quad_perm:[1,0,3,2] row_mask:0xf bank_mask:0xf
	v_cndmask_b32_e32 v180, v148, v190, vcc
	v_cndmask_b32_e32 v181, v149, v191, vcc
	v_cndmask_b32_e32 v182, v190, v150, vcc
	v_cndmask_b32_e32 v183, v191, v151, vcc
	global_store_dwordx4 v177, v[180:183], s[12:13] sc1
	v_cndmask_b32_e32 v188, v154, v152, vcc
	v_cndmask_b32_e32 v189, v155, v153, vcc
	s_nop 1
	v_mov_b32_dpp v190, v188 quad_perm:[1,0,3,2] row_mask:0xf bank_mask:0xf
	v_mov_b32_dpp v191, v189 quad_perm:[1,0,3,2] row_mask:0xf bank_mask:0xf
	v_cndmask_b32_e32 v184, v152, v190, vcc
	v_cndmask_b32_e32 v185, v153, v191, vcc
	v_cndmask_b32_e32 v186, v190, v154, vcc
	v_cndmask_b32_e32 v187, v191, v155, vcc
	global_store_dwordx4 v177, v[184:187], s[12:13] offset:1024 sc1
	s_add_u32 s12, s12, 0x400000
	s_addc_u32 s13, s13, 0
	v_mul_f32_e32 v156, v32, v32
	v_mul_f32_e32 v157, v36, v36
	v_mul_f32_e32 v158, v40, v40
	v_mul_f32_e32 v159, v44, v44
	v_fmac_f32_e32 v156, v33, v33
	v_fmac_f32_e32 v157, v37, v37
	v_fmac_f32_e32 v158, v41, v41
	v_fmac_f32_e32 v159, v45, v45
	v_fmac_f32_e32 v156, v34, v34
	v_fmac_f32_e32 v157, v38, v38
	v_fmac_f32_e32 v158, v42, v42
	v_fmac_f32_e32 v159, v46, v46
	v_fmac_f32_e32 v156, v35, v35
	v_fmac_f32_e32 v157, v39, v39
	v_fmac_f32_e32 v158, v43, v43
	v_fmac_f32_e32 v159, v47, v47
	v_add_f32_e32 v156, v156, v157
	v_add_f32_e32 v158, v158, v159
	v_add_f32_e32 v144, v156, v158
	global_load_dwordx4 v[96:99], v172, s[16:17]
	global_load_dwordx4 v[100:103], v172, s[16:17] offset:1024
	global_load_dwordx4 v[104:107], v172, s[16:17] offset:2048
	global_load_dwordx4 v[108:111], v172, s[16:17] offset:3072
	global_load_dwordx4 v[128:131], v172, s[14:15]
	global_load_dwordx4 v[132:135], v172, s[14:15] offset:1024
	global_load_dwordx4 v[136:139], v172, s[14:15] offset:2048
	global_load_dwordx4 v[140:143], v172, s[14:15] offset:3072
	s_add_u32 s16, s16, 0x6000
	s_addc_u32 s17, s17, 0
	s_add_u32 s14, s14, 0x6000
	s_addc_u32 s15, s15, 0
	s_nop 1
	v_add_f32_dpp v144, v144, v144 quad_perm:[1,0,3,2] row_mask:0xf bank_mask:0xf bound_ctrl:1
	s_nop 1
	v_add_f32_dpp v144, v144, v144 quad_perm:[2,3,0,1] row_mask:0xf bank_mask:0xf bound_ctrl:1
	s_nop 1
	v_add_f32_dpp v144, v144, v144 row_half_mirror row_mask:0xf bank_mask:0xf bound_ctrl:1
	s_nop 1
	v_add_f32_dpp v144, v144, v144 row_mirror row_mask:0xf bank_mask:0xf bound_ctrl:1
	s_nop 1
	ds_bpermute_b32 v145, v174, v144
	s_waitcnt lgkmcnt(0)
	v_add_f32_e32 v144, v144, v145
	ds_bpermute_b32 v145, v175, v144
	s_waitcnt lgkmcnt(0)
	v_add_f32_e32 v144, v144, v145
	v_mov_b32_e32 v145, 0x358637bd
	v_fmac_f32_e32 v145, 0x3a800000, v144
	v_rsq_f32_e32 v146, v145
	s_nop 0
	s_waitcnt vmcnt(10)
	v_add_f32_e32 v80, 1.0, v80
	v_add_f32_e32 v81, 1.0, v81
	v_add_f32_e32 v82, 1.0, v82
	v_add_f32_e32 v83, 1.0, v83
	v_add_f32_e32 v84, 1.0, v84
	v_add_f32_e32 v85, 1.0, v85
	v_add_f32_e32 v86, 1.0, v86
	v_add_f32_e32 v87, 1.0, v87
	v_add_f32_e32 v88, 1.0, v88
	v_add_f32_e32 v89, 1.0, v89
	v_add_f32_e32 v90, 1.0, v90
	v_add_f32_e32 v91, 1.0, v91
	v_add_f32_e32 v92, 1.0, v92
	v_add_f32_e32 v93, 1.0, v93
	v_add_f32_e32 v94, 1.0, v94
	v_add_f32_e32 v95, 1.0, v95
	v_mul_f32_e32 v156, v32, v146
	v_mul_f32_e32 v157, v33, v146
	v_mul_f32_e32 v158, v34, v146
	v_mul_f32_e32 v159, v35, v146
	v_mul_f32_e32 v160, v36, v146
	v_mul_f32_e32 v161, v37, v146
	v_mul_f32_e32 v162, v38, v146
	v_mul_f32_e32 v163, v39, v146
	v_mul_f32_e32 v164, v40, v146
	v_mul_f32_e32 v165, v41, v146
	v_mul_f32_e32 v166, v42, v146
	v_mul_f32_e32 v167, v43, v146
	v_mul_f32_e32 v168, v44, v146
	v_mul_f32_e32 v169, v45, v146
	v_mul_f32_e32 v170, v46, v146
	v_mul_f32_e32 v171, v47, v146
	v_mul_f32_e32 v156, v64, v156
	v_mul_f32_e32 v157, v65, v157
	v_mul_f32_e32 v158, v66, v158
	v_mul_f32_e32 v159, v67, v159
	v_mul_f32_e32 v160, v68, v160
	v_mul_f32_e32 v161, v69, v161
	v_mul_f32_e32 v162, v70, v162
	v_mul_f32_e32 v163, v71, v163
	v_mul_f32_e32 v164, v72, v164
	v_mul_f32_e32 v165, v73, v165
	v_mul_f32_e32 v166, v74, v166
	v_mul_f32_e32 v167, v75, v167
	v_mul_f32_e32 v168, v76, v168
	v_mul_f32_e32 v169, v77, v169
	v_mul_f32_e32 v170, v78, v170
	v_mul_f32_e32 v171, v79, v171
	v_fma_f32 v156, v80, v156, v112
	v_fma_f32 v157, v81, v157, v113
	v_fma_f32 v158, v82, v158, v114
	v_fma_f32 v159, v83, v159, v115
	v_fma_f32 v160, v84, v160, v116
	v_fma_f32 v161, v85, v161, v117
	v_fma_f32 v162, v86, v162, v118
	v_fma_f32 v163, v87, v163, v119
	v_fma_f32 v164, v88, v164, v120
	v_fma_f32 v165, v89, v165, v121
	v_fma_f32 v166, v90, v166, v122
	v_fma_f32 v167, v91, v167, v123
	v_fma_f32 v168, v92, v168, v124
	v_fma_f32 v169, v93, v169, v125
	v_fma_f32 v170, v94, v170, v126
	v_fma_f32 v171, v95, v171, v127
	v_cvt_pk_bf16_f32 v148, v156, v157
	v_cvt_pk_bf16_f32 v149, v158, v159
	v_cvt_pk_bf16_f32 v150, v160, v161
	v_cvt_pk_bf16_f32 v151, v162, v163
	v_cvt_pk_bf16_f32 v152, v164, v165
	v_cvt_pk_bf16_f32 v153, v166, v167
	v_cvt_pk_bf16_f32 v154, v168, v169
	v_cvt_pk_bf16_f32 v155, v170, v171
	v_cndmask_b32_e32 v188, v150, v148, vcc
	v_cndmask_b32_e32 v189, v151, v149, vcc
	s_nop 1
	v_mov_b32_dpp v190, v188 quad_perm:[1,0,3,2] row_mask:0xf bank_mask:0xf
	v_mov_b32_dpp v191, v189 quad_perm:[1,0,3,2] row_mask:0xf bank_mask:0xf
	v_cndmask_b32_e32 v180, v148, v190, vcc
	v_cndmask_b32_e32 v181, v149, v191, vcc
	v_cndmask_b32_e32 v182, v190, v150, vcc
	v_cndmask_b32_e32 v183, v191, v151, vcc
	global_store_dwordx4 v177, v[180:183], s[12:13] sc1
	v_cndmask_b32_e32 v188, v154, v152, vcc
	v_cndmask_b32_e32 v189, v155, v153, vcc
	s_nop 1
	v_mov_b32_dpp v190, v188 quad_perm:[1,0,3,2] row_mask:0xf bank_mask:0xf
	v_mov_b32_dpp v191, v189 quad_perm:[1,0,3,2] row_mask:0xf bank_mask:0xf
	v_cndmask_b32_e32 v184, v152, v190, vcc
	v_cndmask_b32_e32 v185, v153, v191, vcc
	v_cndmask_b32_e32 v186, v190, v154, vcc
	v_cndmask_b32_e32 v187, v191, v155, vcc
	global_store_dwordx4 v177, v[184:187], s[12:13] offset:1024 sc1
	s_add_u32 s12, s12, 0x400000
	s_addc_u32 s13, s13, 0
	v_mul_f32_e32 v156, v48, v48
	v_mul_f32_e32 v157, v52, v52
	v_mul_f32_e32 v158, v56, v56
	v_mul_f32_e32 v159, v60, v60
	v_fmac_f32_e32 v156, v49, v49
	v_fmac_f32_e32 v157, v53, v53
	v_fmac_f32_e32 v158, v57, v57
	v_fmac_f32_e32 v159, v61, v61
	v_fmac_f32_e32 v156, v50, v50
	v_fmac_f32_e32 v157, v54, v54
	v_fmac_f32_e32 v158, v58, v58
	v_fmac_f32_e32 v159, v62, v62
	v_fmac_f32_e32 v156, v51, v51
	v_fmac_f32_e32 v157, v55, v55
	v_fmac_f32_e32 v158, v59, v59
	v_fmac_f32_e32 v159, v63, v63
	v_add_f32_e32 v156, v156, v157
	v_add_f32_e32 v158, v158, v159
	v_add_f32_e32 v144, v156, v158
	s_nop 1
	v_add_f32_dpp v144, v144, v144 quad_perm:[1,0,3,2] row_mask:0xf bank_mask:0xf bound_ctrl:1
	s_nop 1
	v_add_f32_dpp v144, v144, v144 quad_perm:[2,3,0,1] row_mask:0xf bank_mask:0xf bound_ctrl:1
	s_nop 1
	v_add_f32_dpp v144, v144, v144 row_half_mirror row_mask:0xf bank_mask:0xf bound_ctrl:1
	s_nop 1
	v_add_f32_dpp v144, v144, v144 row_mirror row_mask:0xf bank_mask:0xf bound_ctrl:1
	s_nop 1
	ds_bpermute_b32 v145, v174, v144
	s_waitcnt lgkmcnt(0)
	v_add_f32_e32 v144, v144, v145
	ds_bpermute_b32 v145, v175, v144
	s_waitcnt lgkmcnt(0)
	v_add_f32_e32 v144, v144, v145
	v_mov_b32_e32 v145, 0x358637bd
	v_fmac_f32_e32 v145, 0x3a800000, v144
	v_rsq_f32_e32 v146, v145
	s_nop 0
	s_waitcnt vmcnt(2)
	v_add_f32_e32 v96, 1.0, v96
	v_add_f32_e32 v97, 1.0, v97
	v_add_f32_e32 v98, 1.0, v98
	v_add_f32_e32 v99, 1.0, v99
	v_add_f32_e32 v100, 1.0, v100
	v_add_f32_e32 v101, 1.0, v101
	v_add_f32_e32 v102, 1.0, v102
	v_add_f32_e32 v103, 1.0, v103
	v_add_f32_e32 v104, 1.0, v104
	v_add_f32_e32 v105, 1.0, v105
	v_add_f32_e32 v106, 1.0, v106
	v_add_f32_e32 v107, 1.0, v107
	v_add_f32_e32 v108, 1.0, v108
	v_add_f32_e32 v109, 1.0, v109
	v_add_f32_e32 v110, 1.0, v110
	v_add_f32_e32 v111, 1.0, v111
	v_mul_f32_e32 v156, v48, v146
	v_mul_f32_e32 v157, v49, v146
	v_mul_f32_e32 v158, v50, v146
	v_mul_f32_e32 v159, v51, v146
	v_mul_f32_e32 v160, v52, v146
	v_mul_f32_e32 v161, v53, v146
	v_mul_f32_e32 v162, v54, v146
	v_mul_f32_e32 v163, v55, v146
	v_mul_f32_e32 v164, v56, v146
	v_mul_f32_e32 v165, v57, v146
	v_mul_f32_e32 v166, v58, v146
	v_mul_f32_e32 v167, v59, v146
	v_mul_f32_e32 v168, v60, v146
	v_mul_f32_e32 v169, v61, v146
	v_mul_f32_e32 v170, v62, v146
	v_mul_f32_e32 v171, v63, v146
	v_mul_f32_e32 v156, v64, v156
	v_mul_f32_e32 v157, v65, v157
	v_mul_f32_e32 v158, v66, v158
	v_mul_f32_e32 v159, v67, v159
	v_mul_f32_e32 v160, v68, v160
	v_mul_f32_e32 v161, v69, v161
	v_mul_f32_e32 v162, v70, v162
	v_mul_f32_e32 v163, v71, v163
	v_mul_f32_e32 v164, v72, v164
	v_mul_f32_e32 v165, v73, v165
	v_mul_f32_e32 v166, v74, v166
	v_mul_f32_e32 v167, v75, v167
	v_mul_f32_e32 v168, v76, v168
	v_mul_f32_e32 v169, v77, v169
	v_mul_f32_e32 v170, v78, v170
	v_mul_f32_e32 v171, v79, v171
	v_fma_f32 v156, v96, v156, v128
	v_fma_f32 v157, v97, v157, v129
	v_fma_f32 v158, v98, v158, v130
	v_fma_f32 v159, v99, v159, v131
	v_fma_f32 v160, v100, v160, v132
	v_fma_f32 v161, v101, v161, v133
	v_fma_f32 v162, v102, v162, v134
	v_fma_f32 v163, v103, v163, v135
	v_fma_f32 v164, v104, v164, v136
	v_fma_f32 v165, v105, v165, v137
	v_fma_f32 v166, v106, v166, v138
	v_fma_f32 v167, v107, v167, v139
	v_fma_f32 v168, v108, v168, v140
	v_fma_f32 v169, v109, v169, v141
	v_fma_f32 v170, v110, v170, v142
	v_fma_f32 v171, v111, v171, v143
	v_cvt_pk_bf16_f32 v148, v156, v157
	v_cvt_pk_bf16_f32 v149, v158, v159
	v_cvt_pk_bf16_f32 v150, v160, v161
	v_cvt_pk_bf16_f32 v151, v162, v163
	v_cvt_pk_bf16_f32 v152, v164, v165
	v_cvt_pk_bf16_f32 v153, v166, v167
	v_cvt_pk_bf16_f32 v154, v168, v169
	v_cvt_pk_bf16_f32 v155, v170, v171
	v_cndmask_b32_e32 v188, v150, v148, vcc
	v_cndmask_b32_e32 v189, v151, v149, vcc
	s_nop 1
	v_mov_b32_dpp v190, v188 quad_perm:[1,0,3,2] row_mask:0xf bank_mask:0xf
	v_mov_b32_dpp v191, v189 quad_perm:[1,0,3,2] row_mask:0xf bank_mask:0xf
	v_cndmask_b32_e32 v180, v148, v190, vcc
	v_cndmask_b32_e32 v181, v149, v191, vcc
	v_cndmask_b32_e32 v182, v190, v150, vcc
	v_cndmask_b32_e32 v183, v191, v151, vcc
	global_store_dwordx4 v177, v[180:183], s[12:13] sc1
	v_cndmask_b32_e32 v188, v154, v152, vcc
	v_cndmask_b32_e32 v189, v155, v153, vcc
	s_nop 1
	v_mov_b32_dpp v190, v188 quad_perm:[1,0,3,2] row_mask:0xf bank_mask:0xf
	v_mov_b32_dpp v191, v189 quad_perm:[1,0,3,2] row_mask:0xf bank_mask:0xf
	v_cndmask_b32_e32 v184, v152, v190, vcc
	v_cndmask_b32_e32 v185, v153, v191, vcc
	v_cndmask_b32_e32 v186, v190, v154, vcc
	v_cndmask_b32_e32 v187, v191, v155, vcc
	global_store_dwordx4 v177, v[184:187], s[12:13] offset:1024 sc1
	s_add_u32 s12, s12, 0x400000
	s_addc_u32 s13, s13, 0
	s_branch .LBB0_177
	s_nop 0
	s_nop 0
	s_nop 0
	s_nop 0
	s_nop 0
	s_nop 0
	s_nop 0
	s_nop 0
	s_nop 0
	s_nop 0
	s_nop 0
.Lnorm1_generic:
	v_mbcnt_lo_u32_b32 v1, -1, 0
	v_mbcnt_hi_u32_b32 v1, -1, v1
	v_and_b32_e32 v3, 64, v1
	v_xor_b32_e32 v2, 16, v1
	v_add_u32_e32 v3, 64, v3
	v_cmp_lt_i32_e32 vcc, v2, v3
	s_add_u32 s26, s3, 0x2800000
	s_addc_u32 s27, s6, 0
	v_cndmask_b32_e32 v2, v1, v2, vcc
	v_mbcnt_lo_u32_b32 v0, s2, 0
	v_lshlrev_b32_e32 v22, 2, v2
	v_xor_b32_e32 v2, 32, v1
	s_add_u32 s28, s3, 0x1c00000
	v_mbcnt_hi_u32_b32 v0, s2, v0
	v_cmp_lt_i32_e32 vcc, v2, v3
	s_addc_u32 s29, s6, 0
	v_mov_b32_e32 v3, 0
	v_cndmask_b32_e32 v1, v1, v2, vcc
	v_lshlrev_b32_e32 v2, 4, v0
	s_ashr_i32 s85, s84, 31
	s_lshl_b32 s2, s76, 4
	v_lshl_add_u64 v[20:21], s[4:5], 0, v[2:3]
	s_lshl_b64 s[4:5], s[84:85], 11
	s_add_u32 s3, s3, s4
	s_addc_u32 s5, s6, s5
	s_add_u32 s4, s3, 0x2800000
	s_addc_u32 s5, s5, 0
	s_ashr_i32 s3, s2, 31
	v_lshlrev_b32_e32 v4, 2, v0
	s_lshl_b64 s[6:7], s[2:3], 11
	s_lshl_b64 s[10:11], s[84:85], 12
	v_add_u32_e32 v2, 0x100, v4
	v_or_b32_e32 v6, 0x200, v4
	v_add_u32_e32 v8, 0x300, v4
	s_add_u32 s10, s24, s10
	v_lshlrev_b32_e32 v23, 2, v1
	s_addc_u32 s11, s25, s11
	s_lshl_b64 s[12:13], s[2:3], 12
	v_lshlrev_b32_e32 v24, 4, v0
	v_mov_b32_e32 v25, 0x358637bd
	s_mov_b32 s3, 0x800000
	v_lshlrev_b32_e32 v26, 3, v0
	v_lshlrev_b32_e32 v27, 2, v4
	s_movk_i32 s30, 0x7fff
	s_mov_b32 s31, 0xffff0000
	v_lshlrev_b32_e32 v28, 2, v2
	v_lshlrev_b32_e32 v29, 2, v6
	v_lshlrev_b32_e32 v30, 2, v8
	s_mov_b32 s34, s84
	s_branch .LBB0_175

.LBB0_651:
	s_or_b64 exec, exec, s[0:1]
	s_add_i32 s0, 0, 0x23fa0
	v_mov_b32_e32 v0, s0
	s_add_i32 s0, 0, 0x23f78
	s_mov_b32 s4, -1
	v_mov_b32_e32 v4, s0
	s_barrier
	ds_read_b128 v[0:3], v0
	ds_read_b64 v[4:5], v4
	s_cmpk_gt_u32 s75, 0xfff
	s_waitcnt lgkmcnt(0)
	v_readfirstlane_b32 s12, v0
	v_readfirstlane_b32 s13, v1
	v_readfirstlane_b32 s0, v4
	v_readfirstlane_b32 s1, v5
	v_readfirstlane_b32 s2, v2
	v_readfirstlane_b32 s3, v3
	s_cbranch_scc1 .LBB0_656
	s_lshl_b32 s14, s25, 8
	s_add_i32 s14, s14, s24
	s_add_i32 s14, s14, s79
	s_ashr_i32 s15, s14, 31
	s_lshl_b64 s[4:5], s[14:15], 12
	s_add_u32 s4, s12, s4
	s_addc_u32 s5, s13, s5
	s_lshl_b64 s[6:7], s[14:15], 11
	s_add_u32 s6, s2, s6
	s_addc_u32 s7, s3, s7
	s_add_u32 s6, s6, 0x2800000
	s_addc_u32 s7, s7, 0
	s_lshr_b32 s16, s25, 3
	s_mul_i32 s16, s16, 0x6000
	s_add_u32 s8, s2, s16
	s_addc_u32 s9, s3, 0
	s_add_u32 s8, s8, 0x1c03000
	s_addc_u32 s9, s9, 0
	s_add_u32 s10, s8, 0x1000
	s_addc_u32 s11, s9, 0
	v_mbcnt_lo_u32_b32 v176, -1, 0
	v_mbcnt_hi_u32_b32 v176, -1, v176
	v_lshlrev_b32_e32 v172, 4, v176
	v_lshlrev_b32_e32 v173, 3, v176
	v_xor_b32_e32 v174, 16, v176
	v_xor_b32_e32 v175, 32, v176
	v_lshlrev_b32_e32 v174, 2, v174
	v_lshlrev_b32_e32 v175, 2, v175
	v_and_b32_e32 v177, 1, v176
	v_cmp_eq_u32_e32 vcc, 1, v177
	v_mul_u32_u24_e32 v177, 0x1f8, v177
	v_add_u32_e32 v177, v177, v173
	global_load_dwordx4 v[0:3], v172, s[4:5]
	global_load_dwordx4 v[4:7], v172, s[4:5] offset:1024
	global_load_dwordx4 v[8:11], v172, s[4:5] offset:2048
	global_load_dwordx4 v[12:15], v172, s[4:5] offset:3072
	s_add_u32 s4, s4, 0x8000
	s_addc_u32 s5, s5, 0
	global_load_dwordx4 v[16:19], v172, s[4:5]
	global_load_dwordx4 v[20:23], v172, s[4:5] offset:1024
	global_load_dwordx4 v[24:27], v172, s[4:5] offset:2048
	global_load_dwordx4 v[28:31], v172, s[4:5] offset:3072
	s_add_u32 s4, s4, 0x8000
	s_addc_u32 s5, s5, 0
	global_load_dwordx4 v[64:67], v172, s[0:1]
	global_load_dwordx4 v[68:71], v172, s[0:1] offset:1024
	global_load_dwordx4 v[72:75], v172, s[0:1] offset:2048
	global_load_dwordx4 v[76:79], v172, s[0:1] offset:3072
	global_load_dwordx4 v[80:83], v172, s[10:11]
	global_load_dwordx4 v[84:87], v172, s[10:11] offset:1024
	global_load_dwordx4 v[88:91], v172, s[10:11] offset:2048
	global_load_dwordx4 v[92:95], v172, s[10:11] offset:3072
	global_load_dwordx4 v[112:115], v172, s[8:9]
	global_load_dwordx4 v[116:119], v172, s[8:9] offset:1024
	global_load_dwordx4 v[120:123], v172, s[8:9] offset:2048
	global_load_dwordx4 v[124:127], v172, s[8:9] offset:3072
	global_load_dwordx4 v[32:35], v172, s[4:5]
	global_load_dwordx4 v[36:39], v172, s[4:5] offset:1024
	global_load_dwordx4 v[40:43], v172, s[4:5] offset:2048
	global_load_dwordx4 v[44:47], v172, s[4:5] offset:3072
	s_add_u32 s4, s4, 0x8000
	s_addc_u32 s5, s5, 0
	global_load_dwordx4 v[48:51], v172, s[4:5]
	global_load_dwordx4 v[52:55], v172, s[4:5] offset:1024
	global_load_dwordx4 v[56:59], v172, s[4:5] offset:2048
	global_load_dwordx4 v[60:63], v172, s[4:5] offset:3072
	s_add_u32 s4, s4, 0x8000
	s_addc_u32 s5, s5, 0
	s_waitcnt vmcnt(24)
	v_mul_f32_e32 v156, v0, v0
	v_mul_f32_e32 v157, v4, v4
	v_mul_f32_e32 v158, v8, v8
	v_mul_f32_e32 v159, v12, v12
	v_fmac_f32_e32 v156, v1, v1
	v_fmac_f32_e32 v157, v5, v5
	v_fmac_f32_e32 v158, v9, v9
	v_fmac_f32_e32 v159, v13, v13
	v_fmac_f32_e32 v156, v2, v2
	v_fmac_f32_e32 v157, v6, v6
	v_fmac_f32_e32 v158, v10, v10
	v_fmac_f32_e32 v159, v14, v14
	v_fmac_f32_e32 v156, v3, v3
	v_fmac_f32_e32 v157, v7, v7
	v_fmac_f32_e32 v158, v11, v11
	v_fmac_f32_e32 v159, v15, v15
	v_add_f32_e32 v156, v156, v157
	v_add_f32_e32 v158, v158, v159
	v_add_f32_e32 v144, v156, v158
	s_nop 1
	v_add_f32_dpp v144, v144, v144 quad_perm:[1,0,3,2] row_mask:0xf bank_mask:0xf bound_ctrl:1
	s_nop 1
	v_add_f32_dpp v144, v144, v144 quad_perm:[2,3,0,1] row_mask:0xf bank_mask:0xf bound_ctrl:1
	s_nop 1
	v_add_f32_dpp v144, v144, v144 row_half_mirror row_mask:0xf bank_mask:0xf bound_ctrl:1
	s_nop 1
	v_add_f32_dpp v144, v144, v144 row_mirror row_mask:0xf bank_mask:0xf bound_ctrl:1
	s_nop 1
	ds_bpermute_b32 v145, v174, v144
	s_waitcnt lgkmcnt(0)
	v_add_f32_e32 v144, v144, v145
	ds_bpermute_b32 v145, v175, v144
	s_waitcnt lgkmcnt(0)
	v_add_f32_e32 v144, v144, v145
	v_mov_b32_e32 v145, 0x358637bd
	v_fmac_f32_e32 v145, 0x3a800000, v144
	v_rsq_f32_e32 v146, v145
	s_nop 0
	s_waitcnt vmcnt(16)
	s_waitcnt vmcnt(8)
	v_add_f32_e32 v80, 1.0, v80
	v_add_f32_e32 v81, 1.0, v81
	v_add_f32_e32 v82, 1.0, v82
	v_add_f32_e32 v83, 1.0, v83
	v_add_f32_e32 v84, 1.0, v84
	v_add_f32_e32 v85, 1.0, v85
	v_add_f32_e32 v86, 1.0, v86
	v_add_f32_e32 v87, 1.0, v87
	v_add_f32_e32 v88, 1.0, v88
	v_add_f32_e32 v89, 1.0, v89
	v_add_f32_e32 v90, 1.0, v90
	v_add_f32_e32 v91, 1.0, v91
	v_add_f32_e32 v92, 1.0, v92
	v_add_f32_e32 v93, 1.0, v93
	v_add_f32_e32 v94, 1.0, v94
	v_add_f32_e32 v95, 1.0, v95
	v_mul_f32_e32 v156, v0, v146
	v_mul_f32_e32 v157, v1, v146
	v_mul_f32_e32 v158, v2, v146
	v_mul_f32_e32 v159, v3, v146
	v_mul_f32_e32 v160, v4, v146
	v_mul_f32_e32 v161, v5, v146
	v_mul_f32_e32 v162, v6, v146
	v_mul_f32_e32 v163, v7, v146
	v_mul_f32_e32 v164, v8, v146
	v_mul_f32_e32 v165, v9, v146
	v_mul_f32_e32 v166, v10, v146
	v_mul_f32_e32 v167, v11, v146
	v_mul_f32_e32 v168, v12, v146
	v_mul_f32_e32 v169, v13, v146
	v_mul_f32_e32 v170, v14, v146
	v_mul_f32_e32 v171, v15, v146
	v_mul_f32_e32 v156, v64, v156
	v_mul_f32_e32 v157, v65, v157
	v_mul_f32_e32 v158, v66, v158
	v_mul_f32_e32 v159, v67, v159
	v_mul_f32_e32 v160, v68, v160
	v_mul_f32_e32 v161, v69, v161
	v_mul_f32_e32 v162, v70, v162
	v_mul_f32_e32 v163, v71, v163
	v_mul_f32_e32 v164, v72, v164
	v_mul_f32_e32 v165, v73, v165
	v_mul_f32_e32 v166, v74, v166
	v_mul_f32_e32 v167, v75, v167
	v_mul_f32_e32 v168, v76, v168
	v_mul_f32_e32 v169, v77, v169
	v_mul_f32_e32 v170, v78, v170
	v_mul_f32_e32 v171, v79, v171
	v_fma_f32 v156, v80, v156, v112
	v_fma_f32 v157, v81, v157, v113
	v_fma_f32 v158, v82, v158, v114
	v_fma_f32 v159, v83, v159, v115
	v_fma_f32 v160, v84, v160, v116
	v_fma_f32 v161, v85, v161, v117
	v_fma_f32 v162, v86, v162, v118
	v_fma_f32 v163, v87, v163, v119
	v_fma_f32 v164, v88, v164, v120
	v_fma_f32 v165, v89, v165, v121
	v_fma_f32 v166, v90, v166, v122
	v_fma_f32 v167, v91, v167, v123
	v_fma_f32 v168, v92, v168, v124
	v_fma_f32 v169, v93, v169, v125
	v_fma_f32 v170, v94, v170, v126
	v_fma_f32 v171, v95, v171, v127
	global_load_dwordx4 v[0:3], v172, s[4:5]
	global_load_dwordx4 v[4:7], v172, s[4:5] offset:1024
	global_load_dwordx4 v[8:11], v172, s[4:5] offset:2048
	global_load_dwordx4 v[12:15], v172, s[4:5] offset:3072
	s_add_u32 s4, s4, 0x8000
	s_addc_u32 s5, s5, 0
	v_cvt_pk_bf16_f32 v148, v156, v157
	v_cvt_pk_bf16_f32 v149, v158, v159
	v_cvt_pk_bf16_f32 v150, v160, v161
	v_cvt_pk_bf16_f32 v151, v162, v163
	v_cvt_pk_bf16_f32 v152, v164, v165
	v_cvt_pk_bf16_f32 v153, v166, v167
	v_cvt_pk_bf16_f32 v154, v168, v169
	v_cvt_pk_bf16_f32 v155, v170, v171
	v_cndmask_b32_e32 v188, v150, v148, vcc
	v_cndmask_b32_e32 v189, v151, v149, vcc
	s_nop 1
	v_mov_b32_dpp v190, v188 quad_perm:[1,0,3,2] row_mask:0xf bank_mask:0xf
	v_mov_b32_dpp v191, v189 quad_perm:[1,0,3,2] row_mask:0xf bank_mask:0xf
	v_cndmask_b32_e32 v180, v148, v190, vcc
	v_cndmask_b32_e32 v181, v149, v191, vcc
	v_cndmask_b32_e32 v182, v190, v150, vcc
	v_cndmask_b32_e32 v183, v191, v151, vcc
	global_store_dwordx4 v177, v[180:183], s[6:7] sc1
	v_cndmask_b32_e32 v188, v154, v152, vcc
	v_cndmask_b32_e32 v189, v155, v153, vcc
	s_nop 1
	v_mov_b32_dpp v190, v188 quad_perm:[1,0,3,2] row_mask:0xf bank_mask:0xf
	v_mov_b32_dpp v191, v189 quad_perm:[1,0,3,2] row_mask:0xf bank_mask:0xf
	v_cndmask_b32_e32 v184, v152, v190, vcc
	v_cndmask_b32_e32 v185, v153, v191, vcc
	v_cndmask_b32_e32 v186, v190, v154, vcc
	v_cndmask_b32_e32 v187, v191, v155, vcc
	global_store_dwordx4 v177, v[184:187], s[6:7] offset:1024 sc1
	s_add_u32 s6, s6, 0x4000
	s_addc_u32 s7, s7, 0
	v_mul_f32_e32 v156, v16, v16
	v_mul_f32_e32 v157, v20, v20
	v_mul_f32_e32 v158, v24, v24
	v_mul_f32_e32 v159, v28, v28
	v_fmac_f32_e32 v156, v17, v17
	v_fmac_f32_e32 v157, v21, v21
	v_fmac_f32_e32 v158, v25, v25
	v_fmac_f32_e32 v159, v29, v29
	v_fmac_f32_e32 v156, v18, v18
	v_fmac_f32_e32 v157, v22, v22
	v_fmac_f32_e32 v158, v26, v26
	v_fmac_f32_e32 v159, v30, v30
	v_fmac_f32_e32 v156, v19, v19
	v_fmac_f32_e32 v157, v23, v23
	v_fmac_f32_e32 v158, v27, v27
	v_fmac_f32_e32 v159, v31, v31
	v_add_f32_e32 v156, v156, v157
	v_add_f32_e32 v158, v158, v159
	v_add_f32_e32 v144, v156, v158
	s_nop 1
	v_add_f32_dpp v144, v144, v144 quad_perm:[1,0,3,2] row_mask:0xf bank_mask:0xf bound_ctrl:1
	s_nop 1
	v_add_f32_dpp v144, v144, v144 quad_perm:[2,3,0,1] row_mask:0xf bank_mask:0xf bound_ctrl:1
	s_nop 1
	v_add_f32_dpp v144, v144, v144 row_half_mirror row_mask:0xf bank_mask:0xf bound_ctrl:1
	s_nop 1
	v_add_f32_dpp v144, v144, v144 row_mirror row_mask:0xf bank_mask:0xf bound_ctrl:1
	s_nop 1
	ds_bpermute_b32 v145, v174, v144
	s_waitcnt lgkmcnt(0)
	v_add_f32_e32 v144, v144, v145
	ds_bpermute_b32 v145, v175, v144
	s_waitcnt lgkmcnt(0)
	v_add_f32_e32 v144, v144, v145
	v_mov_b32_e32 v145, 0x358637bd
	v_fmac_f32_e32 v145, 0x3a800000, v144
	v_rsq_f32_e32 v146, v145
	s_nop 0
	v_mul_f32_e32 v156, v16, v146
	v_mul_f32_e32 v157, v17, v146
	v_mul_f32_e32 v158, v18, v146
	v_mul_f32_e32 v159, v19, v146
	v_mul_f32_e32 v160, v20, v146
	v_mul_f32_e32 v161, v21, v146
	v_mul_f32_e32 v162, v22, v146
	v_mul_f32_e32 v163, v23, v146
	v_mul_f32_e32 v164, v24, v146
	v_mul_f32_e32 v165, v25, v146
	v_mul_f32_e32 v166, v26, v146
	v_mul_f32_e32 v167, v27, v146
	v_mul_f32_e32 v168, v28, v146
	v_mul_f32_e32 v169, v29, v146
	v_mul_f32_e32 v170, v30, v146
	v_mul_f32_e32 v171, v31, v146
	v_mul_f32_e32 v156, v64, v156
	v_mul_f32_e32 v157, v65, v157
	v_mul_f32_e32 v158, v66, v158
	v_mul_f32_e32 v159, v67, v159
	v_mul_f32_e32 v160, v68, v160
	v_mul_f32_e32 v161, v69, v161
	v_mul_f32_e32 v162, v70, v162
	v_mul_f32_e32 v163, v71, v163
	v_mul_f32_e32 v164, v72, v164
	v_mul_f32_e32 v165, v73, v165
	v_mul_f32_e32 v166, v74, v166
	v_mul_f32_e32 v167, v75, v167
	v_mul_f32_e32 v168, v76, v168
	v_mul_f32_e32 v169, v77, v169
	v_mul_f32_e32 v170, v78, v170
	v_mul_f32_e32 v171, v79, v171
	v_fma_f32 v156, v80, v156, v112
	v_fma_f32 v157, v81, v157, v113
	v_fma_f32 v158, v82, v158, v114
	v_fma_f32 v159, v83, v159, v115
	v_fma_f32 v160, v84, v160, v116
	v_fma_f32 v161, v85, v161, v117
	v_fma_f32 v162, v86, v162, v118
	v_fma_f32 v163, v87, v163, v119
	v_fma_f32 v164, v88, v164, v120
	v_fma_f32 v165, v89, v165, v121
	v_fma_f32 v166, v90, v166, v122
	v_fma_f32 v167, v91, v167, v123
	v_fma_f32 v168, v92, v168, v124
	v_fma_f32 v169, v93, v169, v125
	v_fma_f32 v170, v94, v170, v126
	v_fma_f32 v171, v95, v171, v127
	global_load_dwordx4 v[16:19], v172, s[4:5]
	global_load_dwordx4 v[20:23], v172, s[4:5] offset:1024
	global_load_dwordx4 v[24:27], v172, s[4:5] offset:2048
	global_load_dwordx4 v[28:31], v172, s[4:5] offset:3072
	s_add_u32 s4, s4, 0x8000
	s_addc_u32 s5, s5, 0
	v_cvt_pk_bf16_f32 v148, v156, v157
	v_cvt_pk_bf16_f32 v149, v158, v159
	v_cvt_pk_bf16_f32 v150, v160, v161
	v_cvt_pk_bf16_f32 v151, v162, v163
	v_cvt_pk_bf16_f32 v152, v164, v165
	v_cvt_pk_bf16_f32 v153, v166, v167
	v_cvt_pk_bf16_f32 v154, v168, v169
	v_cvt_pk_bf16_f32 v155, v170, v171
	v_cndmask_b32_e32 v188, v150, v148, vcc
	v_cndmask_b32_e32 v189, v151, v149, vcc
	s_nop 1
	v_mov_b32_dpp v190, v188 quad_perm:[1,0,3,2] row_mask:0xf bank_mask:0xf
	v_mov_b32_dpp v191, v189 quad_perm:[1,0,3,2] row_mask:0xf bank_mask:0xf
	v_cndmask_b32_e32 v180, v148, v190, vcc
	v_cndmask_b32_e32 v181, v149, v191, vcc
	v_cndmask_b32_e32 v182, v190, v150, vcc
	v_cndmask_b32_e32 v183, v191, v151, vcc
	global_store_dwordx4 v177, v[180:183], s[6:7] sc1
	v_cndmask_b32_e32 v188, v154, v152, vcc
	v_cndmask_b32_e32 v189, v155, v153, vcc
	s_nop 1
	v_mov_b32_dpp v190, v188 quad_perm:[1,0,3,2] row_mask:0xf bank_mask:0xf
	v_mov_b32_dpp v191, v189 quad_perm:[1,0,3,2] row_mask:0xf bank_mask:0xf
	v_cndmask_b32_e32 v184, v152, v190, vcc
	v_cndmask_b32_e32 v185, v153, v191, vcc
	v_cndmask_b32_e32 v186, v190, v154, vcc
	v_cndmask_b32_e32 v187, v191, v155, vcc
	global_store_dwordx4 v177, v[184:187], s[6:7] offset:1024 sc1
	s_add_u32 s6, s6, 0x4000
	s_addc_u32 s7, s7, 0
	s_waitcnt vmcnt(16)
	v_mul_f32_e32 v156, v32, v32
	v_mul_f32_e32 v157, v36, v36
	v_mul_f32_e32 v158, v40, v40
	v_mul_f32_e32 v159, v44, v44
	v_fmac_f32_e32 v156, v33, v33
	v_fmac_f32_e32 v157, v37, v37
	v_fmac_f32_e32 v158, v41, v41
	v_fmac_f32_e32 v159, v45, v45
	v_fmac_f32_e32 v156, v34, v34
	v_fmac_f32_e32 v157, v38, v38
	v_fmac_f32_e32 v158, v42, v42
	v_fmac_f32_e32 v159, v46, v46
	v_fmac_f32_e32 v156, v35, v35
	v_fmac_f32_e32 v157, v39, v39
	v_fmac_f32_e32 v158, v43, v43
	v_fmac_f32_e32 v159, v47, v47
	v_add_f32_e32 v156, v156, v157
	v_add_f32_e32 v158, v158, v159
	v_add_f32_e32 v144, v156, v158
	s_nop 1
	v_add_f32_dpp v144, v144, v144 quad_perm:[1,0,3,2] row_mask:0xf bank_mask:0xf bound_ctrl:1
	s_nop 1
	v_add_f32_dpp v144, v144, v144 quad_perm:[2,3,0,1] row_mask:0xf bank_mask:0xf bound_ctrl:1
	s_nop 1
	v_add_f32_dpp v144, v144, v144 row_half_mirror row_mask:0xf bank_mask:0xf bound_ctrl:1
	s_nop 1
	v_add_f32_dpp v144, v144, v144 row_mirror row_mask:0xf bank_mask:0xf bound_ctrl:1
	s_nop 1
	ds_bpermute_b32 v145, v174, v144
	s_waitcnt lgkmcnt(0)
	v_add_f32_e32 v144, v144, v145
	ds_bpermute_b32 v145, v175, v144
	s_waitcnt lgkmcnt(0)
	v_add_f32_e32 v144, v144, v145
	v_mov_b32_e32 v145, 0x358637bd
	v_fmac_f32_e32 v145, 0x3a800000, v144
	v_rsq_f32_e32 v146, v145
	s_nop 0
	v_mul_f32_e32 v156, v32, v146
	v_mul_f32_e32 v157, v33, v146
	v_mul_f32_e32 v158, v34, v146
	v_mul_f32_e32 v159, v35, v146
	v_mul_f32_e32 v160, v36, v146
	v_mul_f32_e32 v161, v37, v146
	v_mul_f32_e32 v162, v38, v146
	v_mul_f32_e32 v163, v39, v146
	v_mul_f32_e32 v164, v40, v146
	v_mul_f32_e32 v165, v41, v146
	v_mul_f32_e32 v166, v42, v146
	v_mul_f32_e32 v167, v43, v146
	v_mul_f32_e32 v168, v44, v146
	v_mul_f32_e32 v169, v45, v146
	v_mul_f32_e32 v170, v46, v146
	v_mul_f32_e32 v171, v47, v146
	v_mul_f32_e32 v156, v64, v156
	v_mul_f32_e32 v157, v65, v157
	v_mul_f32_e32 v158, v66, v158
	v_mul_f32_e32 v159, v67, v159
	v_mul_f32_e32 v160, v68, v160
	v_mul_f32_e32 v161, v69, v161
	v_mul_f32_e32 v162, v70, v162
	v_mul_f32_e32 v163, v71, v163
	v_mul_f32_e32 v164, v72, v164
	v_mul_f32_e32 v165, v73, v165
	v_mul_f32_e32 v166, v74, v166
	v_mul_f32_e32 v167, v75, v167
	v_mul_f32_e32 v168, v76, v168
	v_mul_f32_e32 v169, v77, v169
	v_mul_f32_e32 v170, v78, v170
	v_mul_f32_e32 v171, v79, v171
	v_fma_f32 v156, v80, v156, v112
	v_fma_f32 v157, v81, v157, v113
	v_fma_f32 v158, v82, v158, v114
	v_fma_f32 v159, v83, v159, v115
	v_fma_f32 v160, v84, v160, v116
	v_fma_f32 v161, v85, v161, v117
	v_fma_f32 v162, v86, v162, v118
	v_fma_f32 v163, v87, v163, v119
	v_fma_f32 v164, v88, v164, v120
	v_fma_f32 v165, v89, v165, v121
	v_fma_f32 v166, v90, v166, v122
	v_fma_f32 v167, v91, v167, v123
	v_fma_f32 v168, v92, v168, v124
	v_fma_f32 v169, v93, v169, v125
	v_fma_f32 v170, v94, v170, v126
	v_fma_f32 v171, v95, v171, v127
	global_load_dwordx4 v[32:35], v172, s[4:5]
	global_load_dwordx4 v[36:39], v172, s[4:5] offset:1024
	global_load_dwordx4 v[40:43], v172, s[4:5] offset:2048
	global_load_dwordx4 v[44:47], v172, s[4:5] offset:3072
	s_add_u32 s4, s4, 0x8000
	s_addc_u32 s5, s5, 0
	v_cvt_pk_bf16_f32 v148, v156, v157
	v_cvt_pk_bf16_f32 v149, v158, v159
	v_cvt_pk_bf16_f32 v150, v160, v161
	v_cvt_pk_bf16_f32 v151, v162, v163
	v_cvt_pk_bf16_f32 v152, v164, v165
	v_cvt_pk_bf16_f32 v153, v166, v167
	v_cvt_pk_bf16_f32 v154, v168, v169
	v_cvt_pk_bf16_f32 v155, v170, v171
	v_cndmask_b32_e32 v188, v150, v148, vcc
	v_cndmask_b32_e32 v189, v151, v149, vcc
	s_nop 1
	v_mov_b32_dpp v190, v188 quad_perm:[1,0,3,2] row_mask:0xf bank_mask:0xf
	v_mov_b32_dpp v191, v189 quad_perm:[1,0,3,2] row_mask:0xf bank_mask:0xf
	v_cndmask_b32_e32 v180, v148, v190, vcc
	v_cndmask_b32_e32 v181, v149, v191, vcc
	v_cndmask_b32_e32 v182, v190, v150, vcc
	v_cndmask_b32_e32 v183, v191, v151, vcc
	global_store_dwordx4 v177, v[180:183], s[6:7] sc1
	v_cndmask_b32_e32 v188, v154, v152, vcc
	v_cndmask_b32_e32 v189, v155, v153, vcc
	s_nop 1
	v_mov_b32_dpp v190, v188 quad_perm:[1,0,3,2] row_mask:0xf bank_mask:0xf
	v_mov_b32_dpp v191, v189 quad_perm:[1,0,3,2] row_mask:0xf bank_mask:0xf
	v_cndmask_b32_e32 v184, v152, v190, vcc
	v_cndmask_b32_e32 v185, v153, v191, vcc
	v_cndmask_b32_e32 v186, v190, v154, vcc
	v_cndmask_b32_e32 v187, v191, v155, vcc
	global_store_dwordx4 v177, v[184:187], s[6:7] offset:1024 sc1
	s_add_u32 s6, s6, 0x4000
	s_addc_u32 s7, s7, 0
	s_waitcnt vmcnt(18)
	v_mul_f32_e32 v156, v48, v48
	v_mul_f32_e32 v157, v52, v52
	v_mul_f32_e32 v158, v56, v56
	v_mul_f32_e32 v159, v60, v60
	v_fmac_f32_e32 v156, v49, v49
	v_fmac_f32_e32 v157, v53, v53
	v_fmac_f32_e32 v158, v57, v57
	v_fmac_f32_e32 v159, v61, v61
	v_fmac_f32_e32 v156, v50, v50
	v_fmac_f32_e32 v157, v54, v54
	v_fmac_f32_e32 v158, v58, v58
	v_fmac_f32_e32 v159, v62, v62
	v_fmac_f32_e32 v156, v51, v51
	v_fmac_f32_e32 v157, v55, v55
	v_fmac_f32_e32 v158, v59, v59
	v_fmac_f32_e32 v159, v63, v63
	v_add_f32_e32 v156, v156, v157
	v_add_f32_e32 v158, v158, v159
	v_add_f32_e32 v144, v156, v158
	s_nop 1
	v_add_f32_dpp v144, v144, v144 quad_perm:[1,0,3,2] row_mask:0xf bank_mask:0xf bound_ctrl:1
	s_nop 1
	v_add_f32_dpp v144, v144, v144 quad_perm:[2,3,0,1] row_mask:0xf bank_mask:0xf bound_ctrl:1
	s_nop 1
	v_add_f32_dpp v144, v144, v144 row_half_mirror row_mask:0xf bank_mask:0xf bound_ctrl:1
	s_nop 1
	v_add_f32_dpp v144, v144, v144 row_mirror row_mask:0xf bank_mask:0xf bound_ctrl:1
	s_nop 1
	ds_bpermute_b32 v145, v174, v144
	s_waitcnt lgkmcnt(0)
	v_add_f32_e32 v144, v144, v145
	ds_bpermute_b32 v145, v175, v144
	s_waitcnt lgkmcnt(0)
	v_add_f32_e32 v144, v144, v145
	v_mov_b32_e32 v145, 0x358637bd
	v_fmac_f32_e32 v145, 0x3a800000, v144
	v_rsq_f32_e32 v146, v145
	s_nop 0
	v_mul_f32_e32 v156, v48, v146
	v_mul_f32_e32 v157, v49, v146
	v_mul_f32_e32 v158, v50, v146
	v_mul_f32_e32 v159, v51, v146
	v_mul_f32_e32 v160, v52, v146
	v_mul_f32_e32 v161, v53, v146
	v_mul_f32_e32 v162, v54, v146
	v_mul_f32_e32 v163, v55, v146
	v_mul_f32_e32 v164, v56, v146
	v_mul_f32_e32 v165, v57, v146
	v_mul_f32_e32 v166, v58, v146
	v_mul_f32_e32 v167, v59, v146
	v_mul_f32_e32 v168, v60, v146
	v_mul_f32_e32 v169, v61, v146
	v_mul_f32_e32 v170, v62, v146
	v_mul_f32_e32 v171, v63, v146
	v_mul_f32_e32 v156, v64, v156
	v_mul_f32_e32 v157, v65, v157
	v_mul_f32_e32 v158, v66, v158
	v_mul_f32_e32 v159, v67, v159
	v_mul_f32_e32 v160, v68, v160
	v_mul_f32_e32 v161, v69, v161
	v_mul_f32_e32 v162, v70, v162
	v_mul_f32_e32 v163, v71, v163
	v_mul_f32_e32 v164, v72, v164
	v_mul_f32_e32 v165, v73, v165
	v_mul_f32_e32 v166, v74, v166
	v_mul_f32_e32 v167, v75, v167
	v_mul_f32_e32 v168, v76, v168
	v_mul_f32_e32 v169, v77, v169
	v_mul_f32_e32 v170, v78, v170
	v_mul_f32_e32 v171, v79, v171
	v_fma_f32 v156, v80, v156, v112
	v_fma_f32 v157, v81, v157, v113
	v_fma_f32 v158, v82, v158, v114
	v_fma_f32 v159, v83, v159, v115
	v_fma_f32 v160, v84, v160, v116
	v_fma_f32 v161, v85, v161, v117
	v_fma_f32 v162, v86, v162, v118
	v_fma_f32 v163, v87, v163, v119
	v_fma_f32 v164, v88, v164, v120
	v_fma_f32 v165, v89, v165, v121
	v_fma_f32 v166, v90, v166, v122
	v_fma_f32 v167, v91, v167, v123
	v_fma_f32 v168, v92, v168, v124
	v_fma_f32 v169, v93, v169, v125
	v_fma_f32 v170, v94, v170, v126
	v_fma_f32 v171, v95, v171, v127
	global_load_dwordx4 v[48:51], v172, s[4:5]
	global_load_dwordx4 v[52:55], v172, s[4:5] offset:1024
	global_load_dwordx4 v[56:59], v172, s[4:5] offset:2048
	global_load_dwordx4 v[60:63], v172, s[4:5] offset:3072
	s_add_u32 s4, s4, 0x8000
	s_addc_u32 s5, s5, 0
	v_cvt_pk_bf16_f32 v148, v156, v157
	v_cvt_pk_bf16_f32 v149, v158, v159
	v_cvt_pk_bf16_f32 v150, v160, v161
	v_cvt_pk_bf16_f32 v151, v162, v163
	v_cvt_pk_bf16_f32 v152, v164, v165
	v_cvt_pk_bf16_f32 v153, v166, v167
	v_cvt_pk_bf16_f32 v154, v168, v169
	v_cvt_pk_bf16_f32 v155, v170, v171
	v_cndmask_b32_e32 v188, v150, v148, vcc
	v_cndmask_b32_e32 v189, v151, v149, vcc
	s_nop 1
	v_mov_b32_dpp v190, v188 quad_perm:[1,0,3,2] row_mask:0xf bank_mask:0xf
	v_mov_b32_dpp v191, v189 quad_perm:[1,0,3,2] row_mask:0xf bank_mask:0xf
	v_cndmask_b32_e32 v180, v148, v190, vcc
	v_cndmask_b32_e32 v181, v149, v191, vcc
	v_cndmask_b32_e32 v182, v190, v150, vcc
	v_cndmask_b32_e32 v183, v191, v151, vcc
	global_store_dwordx4 v177, v[180:183], s[6:7] sc1
	v_cndmask_b32_e32 v188, v154, v152, vcc
	v_cndmask_b32_e32 v189, v155, v153, vcc
	s_nop 1
	v_mov_b32_dpp v190, v188 quad_perm:[1,0,3,2] row_mask:0xf bank_mask:0xf
	v_mov_b32_dpp v191, v189 quad_perm:[1,0,3,2] row_mask:0xf bank_mask:0xf
	v_cndmask_b32_e32 v184, v152, v190, vcc
	v_cndmask_b32_e32 v185, v153, v191, vcc
	v_cndmask_b32_e32 v186, v190, v154, vcc
	v_cndmask_b32_e32 v187, v191, v155, vcc
	global_store_dwordx4 v177, v[184:187], s[6:7] offset:1024 sc1
	s_add_u32 s6, s6, 0x4000
	s_addc_u32 s7, s7, 0
	s_waitcnt vmcnt(20)
	v_mul_f32_e32 v156, v0, v0
	v_mul_f32_e32 v157, v4, v4
	v_mul_f32_e32 v158, v8, v8
	v_mul_f32_e32 v159, v12, v12
	v_fmac_f32_e32 v156, v1, v1
	v_fmac_f32_e32 v157, v5, v5
	v_fmac_f32_e32 v158, v9, v9
	v_fmac_f32_e32 v159, v13, v13
	v_fmac_f32_e32 v156, v2, v2
	v_fmac_f32_e32 v157, v6, v6
	v_fmac_f32_e32 v158, v10, v10
	v_fmac_f32_e32 v159, v14, v14
	v_fmac_f32_e32 v156, v3, v3
	v_fmac_f32_e32 v157, v7, v7
	v_fmac_f32_e32 v158, v11, v11
	v_fmac_f32_e32 v159, v15, v15
	v_add_f32_e32 v156, v156, v157
	v_add_f32_e32 v158, v158, v159
	v_add_f32_e32 v144, v156, v158
	s_nop 1
	v_add_f32_dpp v144, v144, v144 quad_perm:[1,0,3,2] row_mask:0xf bank_mask:0xf bound_ctrl:1
	s_nop 1
	v_add_f32_dpp v144, v144, v144 quad_perm:[2,3,0,1] row_mask:0xf bank_mask:0xf bound_ctrl:1
	s_nop 1
	v_add_f32_dpp v144, v144, v144 row_half_mirror row_mask:0xf bank_mask:0xf bound_ctrl:1
	s_nop 1
	v_add_f32_dpp v144, v144, v144 row_mirror row_mask:0xf bank_mask:0xf bound_ctrl:1
	s_nop 1
	ds_bpermute_b32 v145, v174, v144
	s_waitcnt lgkmcnt(0)
	v_add_f32_e32 v144, v144, v145
	ds_bpermute_b32 v145, v175, v144
	s_waitcnt lgkmcnt(0)
	v_add_f32_e32 v144, v144, v145
	v_mov_b32_e32 v145, 0x358637bd
	v_fmac_f32_e32 v145, 0x3a800000, v144
	v_rsq_f32_e32 v146, v145
	s_nop 0
	v_mul_f32_e32 v156, v0, v146
	v_mul_f32_e32 v157, v1, v146
	v_mul_f32_e32 v158, v2, v146
	v_mul_f32_e32 v159, v3, v146
	v_mul_f32_e32 v160, v4, v146
	v_mul_f32_e32 v161, v5, v146
	v_mul_f32_e32 v162, v6, v146
	v_mul_f32_e32 v163, v7, v146
	v_mul_f32_e32 v164, v8, v146
	v_mul_f32_e32 v165, v9, v146
	v_mul_f32_e32 v166, v10, v146
	v_mul_f32_e32 v167, v11, v146
	v_mul_f32_e32 v168, v12, v146
	v_mul_f32_e32 v169, v13, v146
	v_mul_f32_e32 v170, v14, v146
	v_mul_f32_e32 v171, v15, v146
	v_mul_f32_e32 v156, v64, v156
	v_mul_f32_e32 v157, v65, v157
	v_mul_f32_e32 v158, v66, v158
	v_mul_f32_e32 v159, v67, v159
	v_mul_f32_e32 v160, v68, v160
	v_mul_f32_e32 v161, v69, v161
	v_mul_f32_e32 v162, v70, v162
	v_mul_f32_e32 v163, v71, v163
	v_mul_f32_e32 v164, v72, v164
	v_mul_f32_e32 v165, v73, v165
	v_mul_f32_e32 v166, v74, v166
	v_mul_f32_e32 v167, v75, v167
	v_mul_f32_e32 v168, v76, v168
	v_mul_f32_e32 v169, v77, v169
	v_mul_f32_e32 v170, v78, v170
	v_mul_f32_e32 v171, v79, v171
	v_fma_f32 v156, v80, v156, v112
	v_fma_f32 v157, v81, v157, v113
	v_fma_f32 v158, v82, v158, v114
	v_fma_f32 v159, v83, v159, v115
	v_fma_f32 v160, v84, v160, v116
	v_fma_f32 v161, v85, v161, v117
	v_fma_f32 v162, v86, v162, v118
	v_fma_f32 v163, v87, v163, v119
	v_fma_f32 v164, v88, v164, v120
	v_fma_f32 v165, v89, v165, v121
	v_fma_f32 v166, v90, v166, v122
	v_fma_f32 v167, v91, v167, v123
	v_fma_f32 v168, v92, v168, v124
	v_fma_f32 v169, v93, v169, v125
	v_fma_f32 v170, v94, v170, v126
	v_fma_f32 v171, v95, v171, v127
	v_cvt_pk_bf16_f32 v148, v156, v157
	v_cvt_pk_bf16_f32 v149, v158, v159
	v_cvt_pk_bf16_f32 v150, v160, v161
	v_cvt_pk_bf16_f32 v151, v162, v163
	v_cvt_pk_bf16_f32 v152, v164, v165
	v_cvt_pk_bf16_f32 v153, v166, v167
	v_cvt_pk_bf16_f32 v154, v168, v169
	v_cvt_pk_bf16_f32 v155, v170, v171
	v_cndmask_b32_e32 v188, v150, v148, vcc
	v_cndmask_b32_e32 v189, v151, v149, vcc
	s_nop 1
	v_mov_b32_dpp v190, v188 quad_perm:[1,0,3,2] row_mask:0xf bank_mask:0xf
	v_mov_b32_dpp v191, v189 quad_perm:[1,0,3,2] row_mask:0xf bank_mask:0xf
	v_cndmask_b32_e32 v180, v148, v190, vcc
	v_cndmask_b32_e32 v181, v149, v191, vcc
	v_cndmask_b32_e32 v182, v190, v150, vcc
	v_cndmask_b32_e32 v183, v191, v151, vcc
	global_store_dwordx4 v177, v[180:183], s[6:7] sc1
	v_cndmask_b32_e32 v188, v154, v152, vcc
	v_cndmask_b32_e32 v189, v155, v153, vcc
	s_nop 1
	v_mov_b32_dpp v190, v188 quad_perm:[1,0,3,2] row_mask:0xf bank_mask:0xf
	v_mov_b32_dpp v191, v189 quad_perm:[1,0,3,2] row_mask:0xf bank_mask:0xf
	v_cndmask_b32_e32 v184, v152, v190, vcc
	v_cndmask_b32_e32 v185, v153, v191, vcc
	v_cndmask_b32_e32 v186, v190, v154, vcc
	v_cndmask_b32_e32 v187, v191, v155, vcc
	global_store_dwordx4 v177, v[184:187], s[6:7] offset:1024 sc1
	s_add_u32 s6, s6, 0x4000
	s_addc_u32 s7, s7, 0
	s_waitcnt vmcnt(16)
	v_mul_f32_e32 v156, v16, v16
	v_mul_f32_e32 v157, v20, v20
	v_mul_f32_e32 v158, v24, v24
	v_mul_f32_e32 v159, v28, v28
	v_fmac_f32_e32 v156, v17, v17
	v_fmac_f32_e32 v157, v21, v21
	v_fmac_f32_e32 v158, v25, v25
	v_fmac_f32_e32 v159, v29, v29
	v_fmac_f32_e32 v156, v18, v18
	v_fmac_f32_e32 v157, v22, v22
	v_fmac_f32_e32 v158, v26, v26
	v_fmac_f32_e32 v159, v30, v30
	v_fmac_f32_e32 v156, v19, v19
	v_fmac_f32_e32 v157, v23, v23
	v_fmac_f32_e32 v158, v27, v27
	v_fmac_f32_e32 v159, v31, v31
	v_add_f32_e32 v156, v156, v157
	v_add_f32_e32 v158, v158, v159
	v_add_f32_e32 v144, v156, v158
	s_nop 1
	v_add_f32_dpp v144, v144, v144 quad_perm:[1,0,3,2] row_mask:0xf bank_mask:0xf bound_ctrl:1
	s_nop 1
	v_add_f32_dpp v144, v144, v144 quad_perm:[2,3,0,1] row_mask:0xf bank_mask:0xf bound_ctrl:1
	s_nop 1
	v_add_f32_dpp v144, v144, v144 row_half_mirror row_mask:0xf bank_mask:0xf bound_ctrl:1
	s_nop 1
	v_add_f32_dpp v144, v144, v144 row_mirror row_mask:0xf bank_mask:0xf bound_ctrl:1
	s_nop 1
	ds_bpermute_b32 v145, v174, v144
	s_waitcnt lgkmcnt(0)
	v_add_f32_e32 v144, v144, v145
	ds_bpermute_b32 v145, v175, v144
	s_waitcnt lgkmcnt(0)
	v_add_f32_e32 v144, v144, v145
	v_mov_b32_e32 v145, 0x358637bd
	v_fmac_f32_e32 v145, 0x3a800000, v144
	v_rsq_f32_e32 v146, v145
	s_nop 0
	v_mul_f32_e32 v156, v16, v146
	v_mul_f32_e32 v157, v17, v146
	v_mul_f32_e32 v158, v18, v146
	v_mul_f32_e32 v159, v19, v146
	v_mul_f32_e32 v160, v20, v146
	v_mul_f32_e32 v161, v21, v146
	v_mul_f32_e32 v162, v22, v146
	v_mul_f32_e32 v163, v23, v146
	v_mul_f32_e32 v164, v24, v146
	v_mul_f32_e32 v165, v25, v146
	v_mul_f32_e32 v166, v26, v146
	v_mul_f32_e32 v167, v27, v146
	v_mul_f32_e32 v168, v28, v146
	v_mul_f32_e32 v169, v29, v146
	v_mul_f32_e32 v170, v30, v146
	v_mul_f32_e32 v171, v31, v146
	v_mul_f32_e32 v156, v64, v156
	v_mul_f32_e32 v157, v65, v157
	v_mul_f32_e32 v158, v66, v158
	v_mul_f32_e32 v159, v67, v159
	v_mul_f32_e32 v160, v68, v160
	v_mul_f32_e32 v161, v69, v161
	v_mul_f32_e32 v162, v70, v162
	v_mul_f32_e32 v163, v71, v163
	v_mul_f32_e32 v164, v72, v164
	v_mul_f32_e32 v165, v73, v165
	v_mul_f32_e32 v166, v74, v166
	v_mul_f32_e32 v167, v75, v167
	v_mul_f32_e32 v168, v76, v168
	v_mul_f32_e32 v169, v77, v169
	v_mul_f32_e32 v170, v78, v170
	v_mul_f32_e32 v171, v79, v171
	v_fma_f32 v156, v80, v156, v112
	v_fma_f32 v157, v81, v157, v113
	v_fma_f32 v158, v82, v158, v114
	v_fma_f32 v159, v83, v159, v115
	v_fma_f32 v160, v84, v160, v116
	v_fma_f32 v161, v85, v161, v117
	v_fma_f32 v162, v86, v162, v118
	v_fma_f32 v163, v87, v163, v119
	v_fma_f32 v164, v88, v164, v120
	v_fma_f32 v165, v89, v165, v121
	v_fma_f32 v166, v90, v166, v122
	v_fma_f32 v167, v91, v167, v123
	v_fma_f32 v168, v92, v168, v124
	v_fma_f32 v169, v93, v169, v125
	v_fma_f32 v170, v94, v170, v126
	v_fma_f32 v171, v95, v171, v127
	v_cvt_pk_bf16_f32 v148, v156, v157
	v_cvt_pk_bf16_f32 v149, v158, v159
	v_cvt_pk_bf16_f32 v150, v160, v161
	v_cvt_pk_bf16_f32 v151, v162, v163
	v_cvt_pk_bf16_f32 v152, v164, v165
	v_cvt_pk_bf16_f32 v153, v166, v167
	v_cvt_pk_bf16_f32 v154, v168, v169
	v_cvt_pk_bf16_f32 v155, v170, v171
	v_cndmask_b32_e32 v188, v150, v148, vcc
	v_cndmask_b32_e32 v189, v151, v149, vcc
	s_nop 1
	v_mov_b32_dpp v190, v188 quad_perm:[1,0,3,2] row_mask:0xf bank_mask:0xf
	v_mov_b32_dpp v191, v189 quad_perm:[1,0,3,2] row_mask:0xf bank_mask:0xf
	v_cndmask_b32_e32 v180, v148, v190, vcc
	v_cndmask_b32_e32 v181, v149, v191, vcc
	v_cndmask_b32_e32 v182, v190, v150, vcc
	v_cndmask_b32_e32 v183, v191, v151, vcc
	global_store_dwordx4 v177, v[180:183], s[6:7] sc1
	v_cndmask_b32_e32 v188, v154, v152, vcc
	v_cndmask_b32_e32 v189, v155, v153, vcc
	s_nop 1
	v_mov_b32_dpp v190, v188 quad_perm:[1,0,3,2] row_mask:0xf bank_mask:0xf
	v_mov_b32_dpp v191, v189 quad_perm:[1,0,3,2] row_mask:0xf bank_mask:0xf
	v_cndmask_b32_e32 v184, v152, v190, vcc
	v_cndmask_b32_e32 v185, v153, v191, vcc
	v_cndmask_b32_e32 v186, v190, v154, vcc
	v_cndmask_b32_e32 v187, v191, v155, vcc
	global_store_dwordx4 v177, v[184:187], s[6:7] offset:1024 sc1
	s_add_u32 s6, s6, 0x4000
	s_addc_u32 s7, s7, 0
	s_waitcnt vmcnt(12)
	v_mul_f32_e32 v156, v32, v32
	v_mul_f32_e32 v157, v36, v36
	v_mul_f32_e32 v158, v40, v40
	v_mul_f32_e32 v159, v44, v44
	v_fmac_f32_e32 v156, v33, v33
	v_fmac_f32_e32 v157, v37, v37
	v_fmac_f32_e32 v158, v41, v41
	v_fmac_f32_e32 v159, v45, v45
	v_fmac_f32_e32 v156, v34, v34
	v_fmac_f32_e32 v157, v38, v38
	v_fmac_f32_e32 v158, v42, v42
	v_fmac_f32_e32 v159, v46, v46
	v_fmac_f32_e32 v156, v35, v35
	v_fmac_f32_e32 v157, v39, v39
	v_fmac_f32_e32 v158, v43, v43
	v_fmac_f32_e32 v159, v47, v47
	v_add_f32_e32 v156, v156, v157
	v_add_f32_e32 v158, v158, v159
	v_add_f32_e32 v144, v156, v158
	s_nop 1
	v_add_f32_dpp v144, v144, v144 quad_perm:[1,0,3,2] row_mask:0xf bank_mask:0xf bound_ctrl:1
	s_nop 1
	v_add_f32_dpp v144, v144, v144 quad_perm:[2,3,0,1] row_mask:0xf bank_mask:0xf bound_ctrl:1
	s_nop 1
	v_add_f32_dpp v144, v144, v144 row_half_mirror row_mask:0xf bank_mask:0xf bound_ctrl:1
	s_nop 1
	v_add_f32_dpp v144, v144, v144 row_mirror row_mask:0xf bank_mask:0xf bound_ctrl:1
	s_nop 1
	ds_bpermute_b32 v145, v174, v144
	s_waitcnt lgkmcnt(0)
	v_add_f32_e32 v144, v144, v145
	ds_bpermute_b32 v145, v175, v144
	s_waitcnt lgkmcnt(0)
	v_add_f32_e32 v144, v144, v145
	v_mov_b32_e32 v145, 0x358637bd
	v_fmac_f32_e32 v145, 0x3a800000, v144
	v_rsq_f32_e32 v146, v145
	s_nop 0
	v_mul_f32_e32 v156, v32, v146
	v_mul_f32_e32 v157, v33, v146
	v_mul_f32_e32 v158, v34, v146
	v_mul_f32_e32 v159, v35, v146
	v_mul_f32_e32 v160, v36, v146
	v_mul_f32_e32 v161, v37, v146
	v_mul_f32_e32 v162, v38, v146
	v_mul_f32_e32 v163, v39, v146
	v_mul_f32_e32 v164, v40, v146
	v_mul_f32_e32 v165, v41, v146
	v_mul_f32_e32 v166, v42, v146
	v_mul_f32_e32 v167, v43, v146
	v_mul_f32_e32 v168, v44, v146
	v_mul_f32_e32 v169, v45, v146
	v_mul_f32_e32 v170, v46, v146
	v_mul_f32_e32 v171, v47, v146
	v_mul_f32_e32 v156, v64, v156
	v_mul_f32_e32 v157, v65, v157
	v_mul_f32_e32 v158, v66, v158
	v_mul_f32_e32 v159, v67, v159
	v_mul_f32_e32 v160, v68, v160
	v_mul_f32_e32 v161, v69, v161
	v_mul_f32_e32 v162, v70, v162
	v_mul_f32_e32 v163, v71, v163
	v_mul_f32_e32 v164, v72, v164
	v_mul_f32_e32 v165, v73, v165
	v_mul_f32_e32 v166, v74, v166
	v_mul_f32_e32 v167, v75, v167
	v_mul_f32_e32 v168, v76, v168
	v_mul_f32_e32 v169, v77, v169
	v_mul_f32_e32 v170, v78, v170
	v_mul_f32_e32 v171, v79, v171
	v_fma_f32 v156, v80, v156, v112
	v_fma_f32 v157, v81, v157, v113
	v_fma_f32 v158, v82, v158, v114
	v_fma_f32 v159, v83, v159, v115
	v_fma_f32 v160, v84, v160, v116
	v_fma_f32 v161, v85, v161, v117
	v_fma_f32 v162, v86, v162, v118
	v_fma_f32 v163, v87, v163, v119
	v_fma_f32 v164, v88, v164, v120
	v_fma_f32 v165, v89, v165, v121
	v_fma_f32 v166, v90, v166, v122
	v_fma_f32 v167, v91, v167, v123
	v_fma_f32 v168, v92, v168, v124
	v_fma_f32 v169, v93, v169, v125
	v_fma_f32 v170, v94, v170, v126
	v_fma_f32 v171, v95, v171, v127
	v_cvt_pk_bf16_f32 v148, v156, v157
	v_cvt_pk_bf16_f32 v149, v158, v159
	v_cvt_pk_bf16_f32 v150, v160, v161
	v_cvt_pk_bf16_f32 v151, v162, v163
	v_cvt_pk_bf16_f32 v152, v164, v165
	v_cvt_pk_bf16_f32 v153, v166, v167
	v_cvt_pk_bf16_f32 v154, v168, v169
	v_cvt_pk_bf16_f32 v155, v170, v171
	v_cndmask_b32_e32 v188, v150, v148, vcc
	v_cndmask_b32_e32 v189, v151, v149, vcc
	s_nop 1
	v_mov_b32_dpp v190, v188 quad_perm:[1,0,3,2] row_mask:0xf bank_mask:0xf
	v_mov_b32_dpp v191, v189 quad_perm:[1,0,3,2] row_mask:0xf bank_mask:0xf
	v_cndmask_b32_e32 v180, v148, v190, vcc
	v_cndmask_b32_e32 v181, v149, v191, vcc
	v_cndmask_b32_e32 v182, v190, v150, vcc
	v_cndmask_b32_e32 v183, v191, v151, vcc
	global_store_dwordx4 v177, v[180:183], s[6:7] sc1
	v_cndmask_b32_e32 v188, v154, v152, vcc
	v_cndmask_b32_e32 v189, v155, v153, vcc
	s_nop 1
	v_mov_b32_dpp v190, v188 quad_perm:[1,0,3,2] row_mask:0xf bank_mask:0xf
	v_mov_b32_dpp v191, v189 quad_perm:[1,0,3,2] row_mask:0xf bank_mask:0xf
	v_cndmask_b32_e32 v184, v152, v190, vcc
	v_cndmask_b32_e32 v185, v153, v191, vcc
	v_cndmask_b32_e32 v186, v190, v154, vcc
	v_cndmask_b32_e32 v187, v191, v155, vcc
	global_store_dwordx4 v177, v[184:187], s[6:7] offset:1024 sc1
	s_add_u32 s6, s6, 0x4000
	s_addc_u32 s7, s7, 0
	s_waitcnt vmcnt(8)
	v_mul_f32_e32 v156, v48, v48
	v_mul_f32_e32 v157, v52, v52
	v_mul_f32_e32 v158, v56, v56
	v_mul_f32_e32 v159, v60, v60
	v_fmac_f32_e32 v156, v49, v49
	v_fmac_f32_e32 v157, v53, v53
	v_fmac_f32_e32 v158, v57, v57
	v_fmac_f32_e32 v159, v61, v61
	v_fmac_f32_e32 v156, v50, v50
	v_fmac_f32_e32 v157, v54, v54
	v_fmac_f32_e32 v158, v58, v58
	v_fmac_f32_e32 v159, v62, v62
	v_fmac_f32_e32 v156, v51, v51
	v_fmac_f32_e32 v157, v55, v55
	v_fmac_f32_e32 v158, v59, v59
	v_fmac_f32_e32 v159, v63, v63
	v_add_f32_e32 v156, v156, v157
	v_add_f32_e32 v158, v158, v159
	v_add_f32_e32 v144, v156, v158
	s_nop 1
	v_add_f32_dpp v144, v144, v144 quad_perm:[1,0,3,2] row_mask:0xf bank_mask:0xf bound_ctrl:1
	s_nop 1
	v_add_f32_dpp v144, v144, v144 quad_perm:[2,3,0,1] row_mask:0xf bank_mask:0xf bound_ctrl:1
	s_nop 1
	v_add_f32_dpp v144, v144, v144 row_half_mirror row_mask:0xf bank_mask:0xf bound_ctrl:1
	s_nop 1
	v_add_f32_dpp v144, v144, v144 row_mirror row_mask:0xf bank_mask:0xf bound_ctrl:1
	s_nop 1
	ds_bpermute_b32 v145, v174, v144
	s_waitcnt lgkmcnt(0)
	v_add_f32_e32 v144, v144, v145
	ds_bpermute_b32 v145, v175, v144
	s_waitcnt lgkmcnt(0)
	v_add_f32_e32 v144, v144, v145
	v_mov_b32_e32 v145, 0x358637bd
	v_fmac_f32_e32 v145, 0x3a800000, v144
	v_rsq_f32_e32 v146, v145
	s_nop 0
	v_mul_f32_e32 v156, v48, v146
	v_mul_f32_e32 v157, v49, v146
	v_mul_f32_e32 v158, v50, v146
	v_mul_f32_e32 v159, v51, v146
	v_mul_f32_e32 v160, v52, v146
	v_mul_f32_e32 v161, v53, v146
	v_mul_f32_e32 v162, v54, v146
	v_mul_f32_e32 v163, v55, v146
	v_mul_f32_e32 v164, v56, v146
	v_mul_f32_e32 v165, v57, v146
	v_mul_f32_e32 v166, v58, v146
	v_mul_f32_e32 v167, v59, v146
	v_mul_f32_e32 v168, v60, v146
	v_mul_f32_e32 v169, v61, v146
	v_mul_f32_e32 v170, v62, v146
	v_mul_f32_e32 v171, v63, v146
	v_mul_f32_e32 v156, v64, v156
	v_mul_f32_e32 v157, v65, v157
	v_mul_f32_e32 v158, v66, v158
	v_mul_f32_e32 v159, v67, v159
	v_mul_f32_e32 v160, v68, v160
	v_mul_f32_e32 v161, v69, v161
	v_mul_f32_e32 v162, v70, v162
	v_mul_f32_e32 v163, v71, v163
	v_mul_f32_e32 v164, v72, v164
	v_mul_f32_e32 v165, v73, v165
	v_mul_f32_e32 v166, v74, v166
	v_mul_f32_e32 v167, v75, v167
	v_mul_f32_e32 v168, v76, v168
	v_mul_f32_e32 v169, v77, v169
	v_mul_f32_e32 v170, v78, v170
	v_mul_f32_e32 v171, v79, v171
	v_fma_f32 v156, v80, v156, v112
	v_fma_f32 v157, v81, v157, v113
	v_fma_f32 v158, v82, v158, v114
	v_fma_f32 v159, v83, v159, v115
	v_fma_f32 v160, v84, v160, v116
	v_fma_f32 v161, v85, v161, v117
	v_fma_f32 v162, v86, v162, v118
	v_fma_f32 v163, v87, v163, v119
	v_fma_f32 v164, v88, v164, v120
	v_fma_f32 v165, v89, v165, v121
	v_fma_f32 v166, v90, v166, v122
	v_fma_f32 v167, v91, v167, v123
	v_fma_f32 v168, v92, v168, v124
	v_fma_f32 v169, v93, v169, v125
	v_fma_f32 v170, v94, v170, v126
	v_fma_f32 v171, v95, v171, v127
	v_cvt_pk_bf16_f32 v148, v156, v157
	v_cvt_pk_bf16_f32 v149, v158, v159
	v_cvt_pk_bf16_f32 v150, v160, v161
	v_cvt_pk_bf16_f32 v151, v162, v163
	v_cvt_pk_bf16_f32 v152, v164, v165
	v_cvt_pk_bf16_f32 v153, v166, v167
	v_cvt_pk_bf16_f32 v154, v168, v169
	v_cvt_pk_bf16_f32 v155, v170, v171
	v_cndmask_b32_e32 v188, v150, v148, vcc
	v_cndmask_b32_e32 v189, v151, v149, vcc
	s_nop 1
	v_mov_b32_dpp v190, v188 quad_perm:[1,0,3,2] row_mask:0xf bank_mask:0xf
	v_mov_b32_dpp v191, v189 quad_perm:[1,0,3,2] row_mask:0xf bank_mask:0xf
	v_cndmask_b32_e32 v180, v148, v190, vcc
	v_cndmask_b32_e32 v181, v149, v191, vcc
	v_cndmask_b32_e32 v182, v190, v150, vcc
	v_cndmask_b32_e32 v183, v191, v151, vcc
	global_store_dwordx4 v177, v[180:183], s[6:7] sc1
	v_cndmask_b32_e32 v188, v154, v152, vcc
	v_cndmask_b32_e32 v189, v155, v153, vcc
	s_nop 1
	v_mov_b32_dpp v190, v188 quad_perm:[1,0,3,2] row_mask:0xf bank_mask:0xf
	v_mov_b32_dpp v191, v189 quad_perm:[1,0,3,2] row_mask:0xf bank_mask:0xf
	v_cndmask_b32_e32 v184, v152, v190, vcc
	v_cndmask_b32_e32 v185, v153, v191, vcc
	v_cndmask_b32_e32 v186, v190, v154, vcc
	v_cndmask_b32_e32 v187, v191, v155, vcc
	global_store_dwordx4 v177, v[184:187], s[6:7] offset:1024 sc1
	s_add_u32 s6, s6, 0x4000
	s_addc_u32 s7, s7, 0
